# LRU passes: gelu-gate rows loaded at sub-tile top, warm-up loads for next sub-tile conv rows; plus sc1 stores and batched epilogue loads
# speedup vs baseline: 1.0134x; 1.0079x over previous
;     __host__ __device__ bool next(int i, Unit& u) const {
;         const long L = (long)i * G + c; if (L >= nwg) return false;
;         int wgid = (int)L; { const int q = nwg / NXCD, r = nwg % NXCD, xcd = wgid % NXCD, off = wgid / NXCD; wgid = (xcd < r ? xcd * (q + 1) : r * (q + 1) + (xcd - r) * q) + off; }
.LBB0_351:
	s_add_i32 s41, s41, 1
	v_readlane_b32 s4, v253, 52
	s_mul_i32 s4, s41, s4
	s_mul_hi_u32 s5, s41, s66
	s_add_i32 s5, s5, s4
	s_mul_i32 s4, s41, s66
	s_add_u32 s4, s4, s22
	s_addc_u32 s5, s5, s42
	v_mov_b64_e32 v[206:207], 0xff
	v_mov_b64_e32 v[210:211], 0x100
	v_cmp_gt_i64_e32 vcc, s[4:5], v[206:207]
	v_cmp_lt_i64_e64 s[6:7], s[4:5], v[210:211]
	s_cbranch_vccnz .LBB0_357
	s_ashr_i32 s5, s4, 31
	s_lshr_b32 s5, s5, 29
	s_add_i32 s12, s4, s5
	s_and_b32 s5, s12, -8
	s_sub_i32 s13, s4, s5
	s_cmp_gt_i32 s13, -1
	s_mov_b64 s[4:5], -1
	s_cbranch_scc0 .LBB0_354
	s_lshl_b32 s18, s13, 5
	s_mov_b64 s[4:5], 0

; __device__ __forceinline__ float bflo(unsigned w) { return __uint_as_float(w << 16); }
; __device__ __forceinline__ float bfhi(unsigned w) { return __uint_as_float(w & 0xffff0000u); }
; template <int PASS> __device__ __forceinline__ void lru_wave_item(LAS unsigned char* lds, LAS unsigned char* vw, int b, int c, int h, const MixP& p, int lane, float (&Hrun)[8], bool cont) {
;     ...
;     for (int st = 0; st < CT / 16; ++st) {
;         const int s0 = c * CT + 16 * st;
;         u32x4 ur[7];
;         {
;             const int sb = s0 + 4 * fq - 3;
; #pragma unroll
;             for (int r = 0; r < 7; ++r) ur[r] = *(const u32x4*)(ub + (size_t)max(sb + r, 0) * P1W);
;         }
;         if (s0 == 0 && fq == 0) {
; #pragma unroll
;             for (int r = 0; r < 3; ++r) ur[r] = (u32x4){0u, 0u, 0u, 0u};
;         }
; #pragma unroll
;         for (int jj = 0; jj < 4; ++jj) {
;             f32x2 o[4] = {bv[0], bv[1], bv[2], bv[3]};
; #pragma unroll
;             for (int k = 0; k < 4; ++k) { const u32x4 uk = ur[jj + k];
;                 o[0] = wv[k][0] * (f32x2){bflo(uk.x), bfhi(uk.x)} + o[0]; o[1] = wv[k][1] * (f32x2){bflo(uk.y), bfhi(uk.y)} + o[1];
;                 o[2] = wv[k][2] * (f32x2){bflo(uk.z), bfhi(uk.z)} + o[2]; o[3] = wv[k][3] * (f32x2){bflo(uk.w), bfhi(uk.w)} + o[3]; }
.LBB0_668:
	s_or_b32 s2, s19, s13
	v_add_u32_e32 v74, s2, v230
	v_cndmask_b32_e64 v50, 0, 1, s[28:29]
	v_max_i32_e32 v54, -1, v74
	v_cmp_ne_u32_e32 vcc, 1, v50
	v_max_i32_e32 v50, 0, v74
	v_add_u32_e32 v54, 1, v54
	v_or_b32_e32 v58, 2, v74
	v_mad_u64_u32 v[50:51], s[20:21], v50, s82, v[196:197]
	v_mad_u64_u32 v[54:55], s[20:21], v54, s82, v[196:197]
	v_max_i32_e32 v58, 0, v58
	global_load_dwordx4 v[50:53], v[50:51], off offset:1024
	v_mad_u64_u32 v[58:59], s[20:21], v58, s82, v[196:197]
	global_load_dwordx4 v[54:57], v[54:55], off offset:1024
	v_or_b32_e32 v62, s2, v229
	global_load_dwordx4 v[58:61], v[58:59], off offset:1024
	v_max_i32_e32 v62, 0, v62
	v_mad_u64_u32 v[62:63], s[20:21], v62, s82, v[196:197]
	global_load_dwordx4 v[62:65], v[62:63], off offset:1024
	v_max_i32_e32 v66, -4, v74
	v_add_u32_e32 v66, 4, v66
	v_mad_u64_u32 v[66:67], s[20:21], v66, s82, v[196:197]
	global_load_dwordx4 v[66:69], v[66:67], off offset:1024
	v_max_i32_e32 v70, -5, v74
	v_add_u32_e32 v70, 5, v70
	v_mad_u64_u32 v[70:71], s[20:21], v70, s82, v[196:197]
	global_load_dwordx4 v[70:73], v[70:71], off offset:1024
	v_max_i32_e32 v74, -6, v74
	v_add_u32_e32 v74, 6, v74
	v_mad_u64_u32 v[74:75], s[20:21], v74, s82, v[196:197]
	global_load_dwordx4 v[74:77], v[74:75], off offset:1024
	s_add_i32 s100, s2, 16
	v_add_u32_e32 v92, s100, v230
	v_max_i32_e32 v93, 0, v92
	v_mad_u64_u32 v[94:95], s[98:99], v93, s82, v[196:197]
	global_load_dword v206, v[94:95], off offset:1024
	v_add_u32_e32 v93, 1, v92
	v_max_i32_e32 v93, 0, v93
	v_mad_u64_u32 v[94:95], s[98:99], v93, s82, v[196:197]
	global_load_dword v206, v[94:95], off offset:1024
	v_add_u32_e32 v93, 2, v92
	v_max_i32_e32 v93, 0, v93
	v_mad_u64_u32 v[94:95], s[98:99], v93, s82, v[196:197]
	global_load_dword v206, v[94:95], off offset:1024
	v_add_u32_e32 v93, 3, v92
	v_max_i32_e32 v93, 0, v93
	v_mad_u64_u32 v[94:95], s[98:99], v93, s82, v[196:197]
	global_load_dword v206, v[94:95], off offset:1024
	v_add_u32_e32 v93, 4, v92
	v_max_i32_e32 v93, 0, v93
	v_mad_u64_u32 v[94:95], s[98:99], v93, s82, v[196:197]
	global_load_dword v206, v[94:95], off offset:1024
	v_add_u32_e32 v93, 5, v92
	v_max_i32_e32 v93, 0, v93
	v_mad_u64_u32 v[94:95], s[98:99], v93, s82, v[196:197]
	global_load_dword v206, v[94:95], off offset:1024
	v_add_u32_e32 v93, 6, v92
	v_max_i32_e32 v93, 0, v93
	v_mad_u64_u32 v[94:95], s[98:99], v93, s82, v[196:197]
	global_load_dword v206, v[94:95], off offset:1024
	s_cmp_eq_u32 s2, 0
	s_cselect_b64 s[16:17], -1, 0
	s_and_b64 s[16:17], s[16:17], s[4:5]
	v_add_u32_e32 v138, v234, v231
	s_mov_b32 s19, 16
	s_mov_b64 s[28:29], 0
	s_and_b64 vcc, exec, vcc
	s_waitcnt vmcnt(12)
	v_cndmask_b32_e64 v81, v57, 0, s[16:17]
	v_cndmask_b32_e64 v57, v53, 0, s[16:17]
	v_cndmask_b32_e64 v53, v51, 0, s[16:17]
	v_cndmask_b32_e64 v51, v50, 0, s[16:17]
	s_waitcnt vmcnt(11)
	v_cndmask_b32_e64 v85, v59, 0, s[16:17]
	v_cndmask_b32_e64 v59, v54, 0, s[16:17]
	v_lshlrev_b32_e32 v50, 16, v51
	v_and_b32_e32 v51, 0xffff0000, v51
	v_cndmask_b32_e64 v89, v61, 0, s[16:17]
	v_cndmask_b32_e64 v83, v58, 0, s[16:17]
	v_cndmask_b32_e64 v61, v55, 0, s[16:17]
	v_cndmask_b32_e64 v55, v52, 0, s[16:17]
	s_waitcnt lgkmcnt(13)
	v_pk_fma_f32 v[50:51], v[10:11], v[50:51], v[42:43]
	v_lshlrev_b32_e32 v52, 16, v53
	v_and_b32_e32 v53, 0xffff0000, v53
	v_lshlrev_b32_e32 v58, 16, v59
	v_and_b32_e32 v59, 0xffff0000, v59
	v_cndmask_b32_e64 v87, v60, 0, s[16:17]
	v_cndmask_b32_e64 v79, v56, 0, s[16:17]
	v_pk_fma_f32 v[52:53], v[12:13], v[52:53], v[44:45]
	v_lshlrev_b32_e32 v54, 16, v55
	v_and_b32_e32 v55, 0xffff0000, v55
	v_lshlrev_b32_e32 v56, 16, v57
	v_and_b32_e32 v57, 0xffff0000, v57
	v_pk_fma_f32 v[50:51], v[18:19], v[58:59], v[50:51]
	v_lshlrev_b32_e32 v60, 16, v61
	v_and_b32_e32 v61, 0xffff0000, v61
	v_lshlrev_b32_e32 v82, 16, v83
	v_and_b32_e32 v83, 0xffff0000, v83
	s_waitcnt lgkmcnt(12)
	v_pk_fma_f32 v[54:55], v[14:15], v[54:55], v[46:47]
	v_pk_fma_f32 v[56:57], v[16:17], v[56:57], v[48:49]
	v_pk_fma_f32 v[52:53], v[20:21], v[60:61], v[52:53]
	v_lshlrev_b32_e32 v78, 16, v79
	v_and_b32_e32 v79, 0xffff0000, v79
	v_lshlrev_b32_e32 v80, 16, v81
	v_and_b32_e32 v81, 0xffff0000, v81
	v_pk_fma_f32 v[50:51], v[26:27], v[82:83], v[50:51]
	v_lshlrev_b32_e32 v84, 16, v85
	v_and_b32_e32 v85, 0xffff0000, v85
	s_waitcnt vmcnt(10)
	v_lshlrev_b32_e32 v90, 16, v62
	v_and_b32_e32 v91, 0xffff0000, v62
	v_pk_fma_f32 v[54:55], v[22:23], v[78:79], v[54:55]
	v_pk_fma_f32 v[56:57], v[24:25], v[80:81], v[56:57]
	v_pk_fma_f32 v[52:53], v[28:29], v[84:85], v[52:53]
	v_lshlrev_b32_e32 v86, 16, v87
	v_and_b32_e32 v87, 0xffff0000, v87
	v_lshlrev_b32_e32 v88, 16, v89
	v_and_b32_e32 v89, 0xffff0000, v89
	v_pk_fma_f32 v[50:51], v[34:35], v[90:91], v[50:51]
	v_lshlrev_b32_e32 v62, 16, v63
	v_and_b32_e32 v63, 0xffff0000, v63
	v_pk_fma_f32 v[54:55], v[30:31], v[86:87], v[54:55]
	v_pk_fma_f32 v[56:57], v[32:33], v[88:89], v[56:57]
	v_pk_fma_f32 v[52:53], v[36:37], v[62:63], v[52:53]
	v_lshlrev_b32_e32 v92, 16, v64
	v_and_b32_e32 v93, 0xffff0000, v64
	v_lshlrev_b32_e32 v64, 16, v65
	v_and_b32_e32 v65, 0xffff0000, v65
	v_cvt_pk_bf16_f32 v50, v50, v51
	v_cvt_pk_bf16_f32 v51, v52, v53
	v_pk_fma_f32 v[54:55], v[38:39], v[92:93], v[54:55]
	v_pk_fma_f32 v[56:57], v[40:41], v[64:65], v[56:57]
	v_cvt_pk_bf16_f32 v52, v54, v55
	v_pk_fma_f32 v[54:55], v[14:15], v[78:79], v[46:47]
	v_cvt_pk_bf16_f32 v53, v56, v57
	ds_write_b128 v247, v[50:53]
	v_pk_fma_f32 v[50:51], v[10:11], v[58:59], v[42:43]
	v_pk_fma_f32 v[52:53], v[12:13], v[60:61], v[44:45]
	v_pk_fma_f32 v[50:51], v[18:19], v[82:83], v[50:51]
	v_pk_fma_f32 v[56:57], v[16:17], v[80:81], v[48:49]
	v_pk_fma_f32 v[52:53], v[20:21], v[84:85], v[52:53]
	v_pk_fma_f32 v[50:51], v[26:27], v[90:91], v[50:51]
	s_waitcnt vmcnt(9)
; #define LAS __attribute__((address_space(3)))
; __device__ __forceinline__ unsigned cvt_pk_bf16(float lo, float hi) { unsigned r; asm volatile("v_cvt_pk_bf16_f32 %0, %1, %2" : "=v"(r) : "v"(lo), "v"(hi)); return r; }
; __device__ __forceinline__ float bflo(unsigned w) { return __uint_as_float(w << 16); }
; __device__ __forceinline__ float bfhi(unsigned w) { return __uint_as_float(w & 0xffff0000u); }
; template <int PASS> __device__ __forceinline__ void lru_wave_item(LAS unsigned char* lds, LAS unsigned char* vw, int b, int c, int h, const MixP& p, int lane, float (&Hrun)[8], bool cont) {
;     ...
;         for (int jj = 0; jj < 4; ++jj) {
;             f32x2 o[4] = {bv[0], bv[1], bv[2], bv[3]};
; #pragma unroll
;             for (int k = 0; k < 4; ++k) { const u32x4 uk = ur[jj + k];
;                 o[0] = wv[k][0] * (f32x2){bflo(uk.x), bfhi(uk.x)} + o[0]; o[1] = wv[k][1] * (f32x2){bflo(uk.y), bfhi(uk.y)} + o[1];
;                 o[2] = wv[k][2] * (f32x2){bflo(uk.z), bfhi(uk.z)} + o[2]; o[3] = wv[k][3] * (f32x2){bflo(uk.w), bfhi(uk.w)} + o[3]; }
;             { u32x4 w; w.x = cvt_pk_bf16(o[0].x, o[0].y); w.y = cvt_pk_bf16(o[1].x, o[1].y); w.z = cvt_pk_bf16(o[2].x, o[2].y); w.w = cvt_pk_bf16(o[3].x, o[3].y);
;               *(LAS u32x4*)(vw + (4 * fq + jj) * WROW + cg * 16) = w; }
;         }
;         f32x4 aR[8], aI[8];
;         bf16x8 af[4];
;         {
; #pragma unroll
;             for (int kk = 0; kk < 4; ++kk) af[kk] = *(const LAS bf16x8*)(vw + fr * WROW + kk * 64 + fq * 16);
; #pragma unroll
;             for (int n = 0; n < 8; ++n) {
;                 aR[n] = (f32x4){0.f, 0.f, 0.f, 0.f}; aI[n] = (f32x4){0.f, 0.f, 0.f, 0.f};
; #pragma unroll
;                 for (int kk = 0; kk < 4; ++kk) {
;                     const bf16x8 ba = *(const LAS bf16x8*)(lds + WA_OFF + (16 * n + fr) * WROW + kk * 64 + fq * 16);
;                     const bf16x8 bx = *(const LAS bf16x8*)(lds + WX_OFF + (16 * n + fr) * WROW + kk * 64 + fq * 16);
;                     aR[n] = __builtin_amdgcn_mfma_f32_16x16x32_bf16(af[kk], ba, aR[n], 0, 0, 0);
;                     aI[n] = __builtin_amdgcn_mfma_f32_16x16x32_bf16(af[kk], bx, aI[n], 0, 0, 0);
;                 }
;             }
	v_lshlrev_b32_e32 v58, 16, v66
	v_and_b32_e32 v59, 0xffff0000, v66
	v_pk_fma_f32 v[54:55], v[22:23], v[86:87], v[54:55]
	v_pk_fma_f32 v[56:57], v[24:25], v[88:89], v[56:57]
	v_pk_fma_f32 v[52:53], v[28:29], v[62:63], v[52:53]
	v_pk_fma_f32 v[50:51], v[34:35], v[58:59], v[50:51]
	v_lshlrev_b32_e32 v60, 16, v67
	v_and_b32_e32 v61, 0xffff0000, v67
	v_pk_fma_f32 v[54:55], v[30:31], v[92:93], v[54:55]
	v_pk_fma_f32 v[56:57], v[32:33], v[64:65], v[56:57]
	v_pk_fma_f32 v[52:53], v[36:37], v[60:61], v[52:53]
	v_lshlrev_b32_e32 v66, 16, v68
	v_and_b32_e32 v67, 0xffff0000, v68
	v_lshlrev_b32_e32 v68, 16, v69
	v_and_b32_e32 v69, 0xffff0000, v69
	v_cvt_pk_bf16_f32 v50, v50, v51
	v_cvt_pk_bf16_f32 v51, v52, v53
	v_pk_fma_f32 v[54:55], v[38:39], v[66:67], v[54:55]
	v_pk_fma_f32 v[56:57], v[40:41], v[68:69], v[56:57]
	v_cvt_pk_bf16_f32 v52, v54, v55
	v_pk_fma_f32 v[54:55], v[14:15], v[86:87], v[46:47]
	v_cvt_pk_bf16_f32 v53, v56, v57
	ds_write_b128 v247, v[50:53] offset:272
	v_pk_fma_f32 v[50:51], v[10:11], v[82:83], v[42:43]
	v_pk_fma_f32 v[52:53], v[12:13], v[84:85], v[44:45]
	v_pk_fma_f32 v[50:51], v[18:19], v[90:91], v[50:51]
	v_pk_fma_f32 v[56:57], v[16:17], v[88:89], v[48:49]
	v_pk_fma_f32 v[52:53], v[20:21], v[62:63], v[52:53]
	v_pk_fma_f32 v[50:51], v[26:27], v[58:59], v[50:51]
	s_waitcnt vmcnt(8)
	v_lshlrev_b32_e32 v78, 16, v70
	v_and_b32_e32 v79, 0xffff0000, v70
	v_pk_fma_f32 v[54:55], v[22:23], v[92:93], v[54:55]
	v_pk_fma_f32 v[56:57], v[24:25], v[64:65], v[56:57]
	v_pk_fma_f32 v[52:53], v[28:29], v[60:61], v[52:53]
	v_pk_fma_f32 v[50:51], v[34:35], v[78:79], v[50:51]
	v_lshlrev_b32_e32 v70, 16, v71
	v_and_b32_e32 v71, 0xffff0000, v71
	v_pk_fma_f32 v[54:55], v[30:31], v[66:67], v[54:55]
	v_pk_fma_f32 v[56:57], v[32:33], v[68:69], v[56:57]
	v_pk_fma_f32 v[52:53], v[36:37], v[70:71], v[52:53]
	v_lshlrev_b32_e32 v80, 16, v72
	v_and_b32_e32 v81, 0xffff0000, v72
	v_lshlrev_b32_e32 v72, 16, v73
	v_and_b32_e32 v73, 0xffff0000, v73
	v_cvt_pk_bf16_f32 v50, v50, v51
	v_cvt_pk_bf16_f32 v51, v52, v53
	v_pk_fma_f32 v[54:55], v[38:39], v[80:81], v[54:55]
	v_pk_fma_f32 v[56:57], v[40:41], v[72:73], v[56:57]
	v_cvt_pk_bf16_f32 v52, v54, v55
	v_pk_fma_f32 v[54:55], v[14:15], v[92:93], v[46:47]
	v_cvt_pk_bf16_f32 v53, v56, v57
	ds_write_b128 v247, v[50:53] offset:544
	v_pk_fma_f32 v[50:51], v[10:11], v[90:91], v[42:43]
	v_pk_fma_f32 v[52:53], v[12:13], v[62:63], v[44:45]
	v_pk_fma_f32 v[50:51], v[18:19], v[58:59], v[50:51]
	v_pk_fma_f32 v[52:53], v[20:21], v[60:61], v[52:53]
	v_pk_fma_f32 v[50:51], v[26:27], v[78:79], v[50:51]
	s_waitcnt vmcnt(7)
	v_lshlrev_b32_e32 v58, 16, v74
	v_and_b32_e32 v59, 0xffff0000, v74
	v_pk_fma_f32 v[56:57], v[16:17], v[64:65], v[48:49]
	v_pk_fma_f32 v[54:55], v[22:23], v[66:67], v[54:55]
	v_pk_fma_f32 v[52:53], v[28:29], v[70:71], v[52:53]
	v_pk_fma_f32 v[50:51], v[34:35], v[58:59], v[50:51]
	v_lshlrev_b32_e32 v58, 16, v75
	v_and_b32_e32 v59, 0xffff0000, v75
	v_pk_fma_f32 v[56:57], v[24:25], v[68:69], v[56:57]
	v_pk_fma_f32 v[54:55], v[30:31], v[80:81], v[54:55]
	v_pk_fma_f32 v[52:53], v[36:37], v[58:59], v[52:53]
	v_lshlrev_b32_e32 v58, 16, v76
	v_and_b32_e32 v59, 0xffff0000, v76
	v_pk_fma_f32 v[56:57], v[32:33], v[72:73], v[56:57]
	v_pk_fma_f32 v[54:55], v[38:39], v[58:59], v[54:55]
	v_lshlrev_b32_e32 v58, 16, v77
	v_and_b32_e32 v59, 0xffff0000, v77
	v_cvt_pk_bf16_f32 v50, v50, v51
	v_pk_fma_f32 v[56:57], v[40:41], v[58:59], v[56:57]
	v_cvt_pk_bf16_f32 v51, v52, v53
	v_cvt_pk_bf16_f32 v52, v54, v55
	v_add_u32_e32 v74, v234, v235
	v_cvt_pk_bf16_f32 v53, v56, v57
	ds_write_b128 v247, v[50:53] offset:816
	v_add_u32_e32 v50, v232, v233
	ds_read_b128 v[110:113], v50
	ds_read_b128 v[82:85], v50 offset:64
	ds_read_b128 v[54:57], v50 offset:128
	ds_read_b128 v[50:53], v50 offset:192
	ds_read_b128 v[58:61], v138
	ds_read_b128 v[62:65], v138 offset:34816
	ds_read_b128 v[66:69], v138 offset:64
	ds_read_b128 v[70:73], v138 offset:34880
	s_waitcnt lgkmcnt(3)
	v_mfma_f32_16x16x32_bf16 v[58:61], v[110:113], v[58:61], 0
	s_waitcnt lgkmcnt(2)
	v_mfma_f32_16x16x32_bf16 v[62:65], v[110:113], v[62:65], 0
	s_waitcnt lgkmcnt(1)
	v_mfma_f32_16x16x32_bf16 v[58:61], v[82:85], v[66:69], v[58:61]
	s_waitcnt lgkmcnt(0)
	v_mfma_f32_16x16x32_bf16 v[62:65], v[82:85], v[70:73], v[62:65]
	ds_read_b128 v[66:69], v138 offset:128
	ds_read_b128 v[70:73], v138 offset:34944
	s_waitcnt lgkmcnt(1)
	v_mfma_f32_16x16x32_bf16 v[58:61], v[54:57], v[66:69], v[58:61]
	s_waitcnt lgkmcnt(0)
	v_mfma_f32_16x16x32_bf16 v[62:65], v[54:57], v[70:73], v[62:65]
	ds_read_b128 v[66:69], v138 offset:192
	ds_read_b128 v[70:73], v138 offset:35008
	s_waitcnt lgkmcnt(1)
	v_mfma_f32_16x16x32_bf16 v[126:129], v[50:53], v[66:69], v[58:61]
	s_waitcnt lgkmcnt(0)
	v_mfma_f32_16x16x32_bf16 v[122:125], v[50:53], v[70:73], v[62:65]
	s_nop 0
	ds_read_b128 v[58:61], v138 offset:4352
	s_nop 0
	ds_read_b128 v[62:65], v138 offset:39168
	ds_read_b128 v[66:69], v138 offset:4416
	ds_read_b128 v[70:73], v138 offset:39232
	v_add_f32_e32 v126, v170, v126
	s_waitcnt lgkmcnt(3)
	v_mfma_f32_16x16x32_bf16 v[58:61], v[110:113], v[58:61], 0
	v_add_f32_e32 v127, v170, v127
	v_mul_f32_e32 v126, 0xbfb8aa3b, v126
	v_mul_f32_e32 v127, 0xbfb8aa3b, v127
	s_waitcnt lgkmcnt(2)
	v_mfma_f32_16x16x32_bf16 v[62:65], v[110:113], v[62:65], 0
	v_exp_f32_e32 v126, v126
	v_exp_f32_e32 v127, v127
	v_add_f32_e32 v122, v174, v122
	s_waitcnt lgkmcnt(1)
	v_mfma_f32_16x16x32_bf16 v[58:61], v[82:85], v[66:69], v[58:61]
	v_add_f32_e32 v126, 1.0, v126
	v_add_f32_e32 v127, 1.0, v127
	v_rcp_f32_e32 v126, v126
	s_waitcnt lgkmcnt(0)
; #define LAS __attribute__((address_space(3)))
; __device__ __forceinline__ float fsig2(float x) { return __builtin_amdgcn_rcpf(1.0f + __builtin_amdgcn_exp2f(-LOG2E * x)); }
; template <int PASS> __device__ __forceinline__ void lru_wave_item(LAS unsigned char* lds, LAS unsigned char* vw, int b, int c, int h, const MixP& p, int lane, float (&Hrun)[8], bool cont) {
;     ...
;             for (int n = 0; n < 8; ++n) {
;                 aR[n] = (f32x4){0.f, 0.f, 0.f, 0.f}; aI[n] = (f32x4){0.f, 0.f, 0.f, 0.f};
; #pragma unroll
;                 for (int kk = 0; kk < 4; ++kk) {
;                     const bf16x8 ba = *(const LAS bf16x8*)(lds + WA_OFF + (16 * n + fr) * WROW + kk * 64 + fq * 16);
;                     const bf16x8 bx = *(const LAS bf16x8*)(lds + WX_OFF + (16 * n + fr) * WROW + kk * 64 + fq * 16);
;                     aR[n] = __builtin_amdgcn_mfma_f32_16x16x32_bf16(af[kk], ba, aR[n], 0, 0, 0);
;                     aI[n] = __builtin_amdgcn_mfma_f32_16x16x32_bf16(af[kk], bx, aI[n], 0, 0, 0);
;                 }
;             }
;         }
; #pragma unroll
;         for (int n = 0; n < 8; ++n) {
;             const f32x4 aVn = __builtin_amdgcn_mfma_f32_16x16x32_bf16(af[n >> 1], idf[n & 1], (f32x4){0.f, 0.f, 0.f, 0.f}, 0, 0, 0);
;             float av[4], bxv[4];
; #pragma unroll
;             for (int j = 0; j < 4; ++j) {
;                 const float r = fsig2(aR[n][j] + pba[n]), ig = fsig2(aI[n][j] + pbx[n]);
;                 const float a = __builtin_amdgcn_exp2f(r * pk8[n]), mult = __builtin_amdgcn_sqrtf(fmaxf(1.0f - a * a, 0.f));
	v_mfma_f32_16x16x32_bf16 v[62:65], v[82:85], v[70:73], v[62:65]
	ds_read_b128 v[66:69], v138 offset:4480
	ds_read_b128 v[70:73], v138 offset:39296
	v_rcp_f32_e32 v127, v127
	v_mul_f32_e32 v126, v176, v126
	s_waitcnt lgkmcnt(1)
	v_mfma_f32_16x16x32_bf16 v[58:61], v[54:57], v[66:69], v[58:61]
	v_add_f32_e32 v123, v174, v123
	v_mul_f32_e32 v127, v176, v127
	v_mul_f32_e32 v122, 0xbfb8aa3b, v122
	s_waitcnt lgkmcnt(0)
	v_mfma_f32_16x16x32_bf16 v[62:65], v[54:57], v[70:73], v[62:65]
	ds_read_b128 v[66:69], v138 offset:4544
	ds_read_b128 v[70:73], v138 offset:39360
	v_mul_f32_e32 v123, 0xbfb8aa3b, v123
	v_exp_f32_e32 v122, v122
	s_waitcnt lgkmcnt(1)
	v_mfma_f32_16x16x32_bf16 v[118:121], v[50:53], v[66:69], v[58:61]
	v_exp_f32_e32 v123, v123
	v_add_f32_e32 v122, 1.0, v122
	v_rcp_f32_e32 v122, v122
	s_waitcnt lgkmcnt(0)
	v_mfma_f32_16x16x32_bf16 v[114:117], v[50:53], v[70:73], v[62:65]
	ds_read_b128 v[58:61], v138 offset:8704
	s_nop 1
	ds_read_b128 v[62:65], v138 offset:43520
	ds_read_b128 v[66:69], v138 offset:8768
	ds_read_b128 v[70:73], v138 offset:43584
	v_add_f32_e32 v123, 1.0, v123
	s_waitcnt lgkmcnt(3)
	v_mfma_f32_16x16x32_bf16 v[58:61], v[110:113], v[58:61], 0
	v_rcp_f32_e32 v123, v123
	v_add_f32_e32 v124, v174, v124
	v_add_f32_e32 v125, v174, v125
	s_waitcnt lgkmcnt(2)
	v_mfma_f32_16x16x32_bf16 v[62:65], v[110:113], v[62:65], 0
	v_mul_f32_e32 v124, 0xbfb8aa3b, v124
	v_mul_f32_e32 v125, 0xbfb8aa3b, v125
	v_exp_f32_e32 v124, v124
	s_waitcnt lgkmcnt(1)
	v_mfma_f32_16x16x32_bf16 v[58:61], v[82:85], v[66:69], v[58:61]
	v_exp_f32_e32 v125, v125
	v_add_f32_e32 v118, v171, v118
	v_add_f32_e32 v119, v171, v119
	s_waitcnt lgkmcnt(0)
	v_mfma_f32_16x16x32_bf16 v[62:65], v[82:85], v[70:73], v[62:65]
	ds_read_b128 v[66:69], v138 offset:8832
	ds_read_b128 v[70:73], v138 offset:43648
	v_add_f32_e32 v124, 1.0, v124
	v_add_f32_e32 v125, 1.0, v125
	s_waitcnt lgkmcnt(1)
	v_mfma_f32_16x16x32_bf16 v[58:61], v[54:57], v[66:69], v[58:61]
	v_mul_f32_e32 v118, 0xbfb8aa3b, v118
	v_mul_f32_e32 v119, 0xbfb8aa3b, v119
	v_rcp_f32_e32 v124, v124
	s_waitcnt lgkmcnt(0)
	v_mfma_f32_16x16x32_bf16 v[62:65], v[54:57], v[70:73], v[62:65]
	ds_read_b128 v[66:69], v138 offset:8896
	ds_read_b128 v[70:73], v138 offset:43712
	v_exp_f32_e32 v118, v118
	v_exp_f32_e32 v119, v119
	s_waitcnt lgkmcnt(1)
	v_mfma_f32_16x16x32_bf16 v[106:109], v[50:53], v[66:69], v[58:61]
	v_add_f32_e32 v118, 1.0, v118
	v_add_f32_e32 v119, 1.0, v119
	v_rcp_f32_e32 v118, v118
	s_waitcnt lgkmcnt(0)
	v_mfma_f32_16x16x32_bf16 v[102:105], v[50:53], v[70:73], v[62:65]
	ds_read_b128 v[58:61], v74
	s_nop 1
	ds_read_b128 v[62:65], v74 offset:34816
	ds_read_b128 v[66:69], v74 offset:64
	ds_read_b128 v[70:73], v74 offset:34880
	v_rcp_f32_e32 v119, v119
	s_waitcnt lgkmcnt(3)
	v_mfma_f32_16x16x32_bf16 v[58:61], v[110:113], v[58:61], 0
	v_add_f32_e32 v114, v175, v114
	v_mul_f32_e32 v118, v177, v118
	v_add_f32_e32 v115, v175, v115
	s_waitcnt lgkmcnt(2)
	v_mfma_f32_16x16x32_bf16 v[62:65], v[110:113], v[62:65], 0
	v_mul_f32_e32 v119, v177, v119
	v_mul_f32_e32 v114, 0xbfb8aa3b, v114
	v_mul_f32_e32 v115, 0xbfb8aa3b, v115
	s_waitcnt lgkmcnt(1)
	v_mfma_f32_16x16x32_bf16 v[58:61], v[82:85], v[66:69], v[58:61]
	v_exp_f32_e32 v114, v114
	v_exp_f32_e32 v115, v115
	v_add_f32_e32 v106, v178, v106
	s_waitcnt lgkmcnt(0)
	v_mfma_f32_16x16x32_bf16 v[62:65], v[82:85], v[70:73], v[62:65]
	ds_read_b128 v[66:69], v74 offset:128
	ds_read_b128 v[70:73], v74 offset:34944
	v_add_f32_e32 v114, 1.0, v114
	v_add_f32_e32 v115, 1.0, v115
	s_waitcnt lgkmcnt(1)
	v_mfma_f32_16x16x32_bf16 v[58:61], v[54:57], v[66:69], v[58:61]
	v_rcp_f32_e32 v114, v114
	v_rcp_f32_e32 v115, v115
	v_add_f32_e32 v107, v178, v107
	s_waitcnt lgkmcnt(0)
	v_mfma_f32_16x16x32_bf16 v[62:65], v[54:57], v[70:73], v[62:65]
	ds_read_b128 v[66:69], v74 offset:192
	ds_read_b128 v[70:73], v74 offset:35008
	v_mul_f32_e32 v106, 0xbfb8aa3b, v106
	v_mul_f32_e32 v107, 0xbfb8aa3b, v107
	s_waitcnt lgkmcnt(1)
	v_mfma_f32_16x16x32_bf16 v[90:93], v[50:53], v[66:69], v[58:61]
	v_exp_f32_e32 v106, v106
	v_exp_f32_e32 v107, v107
	v_add_f32_e32 v102, v180, v102
	s_waitcnt lgkmcnt(0)
	v_mfma_f32_16x16x32_bf16 v[86:89], v[50:53], v[70:73], v[62:65]
	ds_read_b128 v[58:61], v138 offset:17408
	s_nop 1
	ds_read_b128 v[62:65], v138 offset:52224
	ds_read_b128 v[66:69], v138 offset:17472
	ds_read_b128 v[70:73], v138 offset:52288
	v_add_f32_e32 v106, 1.0, v106
	s_waitcnt lgkmcnt(3)
	v_mfma_f32_16x16x32_bf16 v[58:61], v[110:113], v[58:61], 0
	v_add_f32_e32 v107, 1.0, v107
	v_rcp_f32_e32 v106, v106
	v_rcp_f32_e32 v107, v107
	s_waitcnt lgkmcnt(2)
	v_mfma_f32_16x16x32_bf16 v[62:65], v[110:113], v[62:65], 0
	v_add_f32_e32 v103, v180, v103
	v_mul_f32_e32 v106, v182, v106
	v_mul_f32_e32 v107, v182, v107
	s_waitcnt lgkmcnt(1)
	v_mfma_f32_16x16x32_bf16 v[58:61], v[82:85], v[66:69], v[58:61]
	v_mul_f32_e32 v102, 0xbfb8aa3b, v102
	v_mul_f32_e32 v103, 0xbfb8aa3b, v103
	v_exp_f32_e32 v102, v102
	s_waitcnt lgkmcnt(0)
	v_mfma_f32_16x16x32_bf16 v[62:65], v[82:85], v[70:73], v[62:65]
	ds_read_b128 v[66:69], v138 offset:17536
	ds_read_b128 v[70:73], v138 offset:52352
	v_exp_f32_e32 v103, v103
	v_add_f32_e32 v102, 1.0, v102
	s_waitcnt lgkmcnt(1)
	v_mfma_f32_16x16x32_bf16 v[58:61], v[54:57], v[66:69], v[58:61]
	v_add_f32_e32 v103, 1.0, v103
	v_rcp_f32_e32 v102, v102
	v_rcp_f32_e32 v103, v103
	s_waitcnt lgkmcnt(0)
	v_mfma_f32_16x16x32_bf16 v[62:65], v[54:57], v[70:73], v[62:65]
	ds_read_b128 v[66:69], v138 offset:17600
	ds_read_b128 v[70:73], v138 offset:52416
	v_add_f32_e32 v104, v180, v104
	v_add_f32_e32 v105, v180, v105
	s_waitcnt lgkmcnt(1)
; #define LAS __attribute__((address_space(3)))
; __device__ __forceinline__ float fsig2(float x) { return __builtin_amdgcn_rcpf(1.0f + __builtin_amdgcn_exp2f(-LOG2E * x)); }
; template <int PASS> __device__ __forceinline__ void lru_wave_item(LAS unsigned char* lds, LAS unsigned char* vw, int b, int c, int h, const MixP& p, int lane, float (&Hrun)[8], bool cont) {
;     ...
;             for (int n = 0; n < 8; ++n) {
;                 aR[n] = (f32x4){0.f, 0.f, 0.f, 0.f}; aI[n] = (f32x4){0.f, 0.f, 0.f, 0.f};
; #pragma unroll
;                 for (int kk = 0; kk < 4; ++kk) {
;                     const bf16x8 ba = *(const LAS bf16x8*)(lds + WA_OFF + (16 * n + fr) * WROW + kk * 64 + fq * 16);
;                     const bf16x8 bx = *(const LAS bf16x8*)(lds + WX_OFF + (16 * n + fr) * WROW + kk * 64 + fq * 16);
;                     aR[n] = __builtin_amdgcn_mfma_f32_16x16x32_bf16(af[kk], ba, aR[n], 0, 0, 0);
;                     aI[n] = __builtin_amdgcn_mfma_f32_16x16x32_bf16(af[kk], bx, aI[n], 0, 0, 0);
;                 }
;             }
;         }
; #pragma unroll
;         for (int n = 0; n < 8; ++n) {
;             const f32x4 aVn = __builtin_amdgcn_mfma_f32_16x16x32_bf16(af[n >> 1], idf[n & 1], (f32x4){0.f, 0.f, 0.f, 0.f}, 0, 0, 0);
;             float av[4], bxv[4];
; #pragma unroll
;             for (int j = 0; j < 4; ++j) {
;                 const float r = fsig2(aR[n][j] + pba[n]), ig = fsig2(aI[n][j] + pbx[n]);
;                 const float a = __builtin_amdgcn_exp2f(r * pk8[n]), mult = __builtin_amdgcn_sqrtf(fmaxf(1.0f - a * a, 0.f));
	v_mfma_f32_16x16x32_bf16 v[78:81], v[50:53], v[66:69], v[58:61]
	v_mul_f32_e32 v104, 0xbfb8aa3b, v104
	v_mul_f32_e32 v105, 0xbfb8aa3b, v105
	v_exp_f32_e32 v104, v104
	s_waitcnt lgkmcnt(0)
	v_mfma_f32_16x16x32_bf16 v[74:77], v[50:53], v[70:73], v[62:65]
	ds_read_b128 v[58:61], v138 offset:21760
	s_nop 1
	ds_read_b128 v[62:65], v138 offset:56576
	ds_read_b128 v[66:69], v138 offset:21824
	ds_read_b128 v[70:73], v138 offset:56640
	v_exp_f32_e32 v105, v105
	s_waitcnt lgkmcnt(3)
	v_mfma_f32_16x16x32_bf16 v[58:61], v[110:113], v[58:61], 0
	v_add_f32_e32 v104, 1.0, v104
	v_add_f32_e32 v105, 1.0, v105
	v_rcp_f32_e32 v104, v104
	s_waitcnt lgkmcnt(2)
	v_mfma_f32_16x16x32_bf16 v[62:65], v[110:113], v[62:65], 0
	v_add_f32_e32 v90, v179, v90
	v_add_f32_e32 v91, v179, v91
	v_mul_f32_e32 v90, 0xbfb8aa3b, v90
	s_waitcnt lgkmcnt(1)
	v_mfma_f32_16x16x32_bf16 v[58:61], v[82:85], v[66:69], v[58:61]
	v_mul_f32_e32 v91, 0xbfb8aa3b, v91
	v_exp_f32_e32 v90, v90
	v_exp_f32_e32 v91, v91
	s_waitcnt lgkmcnt(0)
	v_mfma_f32_16x16x32_bf16 v[62:65], v[82:85], v[70:73], v[62:65]
	ds_read_b128 v[66:69], v138 offset:21888
	ds_read_b128 v[70:73], v138 offset:56704
	v_add_f32_e32 v90, 1.0, v90
	v_add_f32_e32 v91, 1.0, v91
	s_waitcnt lgkmcnt(1)
	v_mfma_f32_16x16x32_bf16 v[58:61], v[54:57], v[66:69], v[58:61]
	ds_read_b128 v[66:69], v138 offset:21952
	ds_read_b128 v[94:97], v138 offset:56768
	v_rcp_f32_e32 v90, v90
	v_rcp_f32_e32 v91, v91
	s_waitcnt lgkmcnt(2)
	v_mfma_f32_16x16x32_bf16 v[62:65], v[54:57], v[70:73], v[62:65]
	v_add_f32_e32 v86, v181, v86
	v_mul_f32_e32 v90, v183, v90
	v_add_f32_e32 v87, v181, v87
	s_waitcnt lgkmcnt(1)
	v_mfma_f32_16x16x32_bf16 v[70:73], v[50:53], v[66:69], v[58:61]
	v_mul_f32_e32 v91, v183, v91
	v_mul_f32_e32 v86, 0xbfb8aa3b, v86
	v_mul_f32_e32 v87, 0xbfb8aa3b, v87
	s_waitcnt lgkmcnt(0)
	v_mfma_f32_16x16x32_bf16 v[66:69], v[50:53], v[94:97], v[62:65]
	ds_read_b128 v[58:61], v138 offset:26112
	s_nop 1
	ds_read_b128 v[62:65], v138 offset:60928
	ds_read_b128 v[94:97], v138 offset:26176
	ds_read_b128 v[98:101], v138 offset:60992
	v_exp_f32_e32 v86, v86
	s_waitcnt lgkmcnt(3)
	v_mfma_f32_16x16x32_bf16 v[58:61], v[110:113], v[58:61], 0
	v_exp_f32_e32 v87, v87
	v_add_f32_e32 v86, 1.0, v86
	v_rcp_f32_e32 v86, v86
	s_waitcnt lgkmcnt(2)
	v_mfma_f32_16x16x32_bf16 v[62:65], v[110:113], v[62:65], 0
	v_add_f32_e32 v87, 1.0, v87
	v_rcp_f32_e32 v87, v87
	v_add_f32_e32 v78, v184, v78
	s_waitcnt lgkmcnt(1)
	v_mfma_f32_16x16x32_bf16 v[58:61], v[82:85], v[94:97], v[58:61]
	v_add_f32_e32 v79, v184, v79
	v_mul_f32_e32 v78, 0xbfb8aa3b, v78
	v_mul_f32_e32 v79, 0xbfb8aa3b, v79
	s_waitcnt lgkmcnt(0)
	v_mfma_f32_16x16x32_bf16 v[62:65], v[82:85], v[98:101], v[62:65]
	ds_read_b128 v[94:97], v138 offset:26240
	ds_read_b128 v[98:101], v138 offset:61056
	v_exp_f32_e32 v78, v78
	v_exp_f32_e32 v79, v79
	s_waitcnt lgkmcnt(1)
	v_mfma_f32_16x16x32_bf16 v[58:61], v[54:57], v[94:97], v[58:61]
	v_add_f32_e32 v78, 1.0, v78
	v_add_f32_e32 v79, 1.0, v79
	v_rcp_f32_e32 v78, v78
	s_waitcnt lgkmcnt(0)
	v_mfma_f32_16x16x32_bf16 v[94:97], v[54:57], v[98:101], v[62:65]
	s_nop 2
	ds_read_b128 v[62:65], v138 offset:26304
	ds_read_b128 v[98:101], v138 offset:61120
	v_rcp_f32_e32 v79, v79
	v_add_f32_e32 v74, v186, v74
	s_waitcnt lgkmcnt(1)
	v_mfma_f32_16x16x32_bf16 v[62:65], v[50:53], v[62:65], v[58:61]
	v_mul_f32_e32 v78, v188, v78
	v_add_f32_e32 v75, v186, v75
	v_mul_f32_e32 v79, v188, v79
	s_waitcnt lgkmcnt(0)
	v_mfma_f32_16x16x32_bf16 v[58:61], v[50:53], v[98:101], v[94:97]
	v_mul_f32_e32 v74, 0xbfb8aa3b, v74
	v_mul_f32_e32 v75, 0xbfb8aa3b, v75
	v_exp_f32_e32 v74, v74
	v_add_u32_e32 v94, v234, v236
	ds_read_b128 v[96:99], v94
	ds_read_b128 v[198:201], v94 offset:34816
	ds_read_b128 v[202:205], v94 offset:64
	ds_read_b128 v[138:141], v94 offset:34880
	s_waitcnt lgkmcnt(3)
	v_mfma_f32_16x16x32_bf16 v[96:99], v[110:113], v[96:99], 0
	v_exp_f32_e32 v75, v75
	v_add_f32_e32 v74, 1.0, v74
	v_rcp_f32_e32 v74, v74
	s_waitcnt lgkmcnt(2)
	v_mfma_f32_16x16x32_bf16 v[198:201], v[110:113], v[198:201], 0
	v_add_f32_e32 v75, 1.0, v75
	v_rcp_f32_e32 v75, v75
	v_add_f32_e32 v76, v186, v76
	s_waitcnt lgkmcnt(1)
	v_mfma_f32_16x16x32_bf16 v[96:99], v[82:85], v[202:205], v[96:99]
	v_add_f32_e32 v77, v186, v77
	v_mul_f32_e32 v76, 0xbfb8aa3b, v76
	v_mul_f32_e32 v77, 0xbfb8aa3b, v77
	s_waitcnt lgkmcnt(0)
	v_mfma_f32_16x16x32_bf16 v[138:141], v[82:85], v[138:141], v[198:201]
	s_nop 2
	ds_read_b128 v[198:201], v94 offset:128
	ds_read_b128 v[202:205], v94 offset:34944
	v_exp_f32_e32 v76, v76
	v_exp_f32_e32 v77, v77
	s_waitcnt lgkmcnt(1)
	v_mfma_f32_16x16x32_bf16 v[96:99], v[54:57], v[198:201], v[96:99]
	v_add_f32_e32 v76, 1.0, v76
	v_add_f32_e32 v77, 1.0, v77
	v_rcp_f32_e32 v76, v76
	s_waitcnt lgkmcnt(0)
	v_mfma_f32_16x16x32_bf16 v[138:141], v[54:57], v[202:205], v[138:141]
	ds_read_b128 v[198:201], v94 offset:192
	ds_read_b128 v[202:205], v94 offset:35008
	v_add_f32_e32 v70, v185, v70
	v_add_f32_e32 v71, v185, v71
	s_waitcnt lgkmcnt(1)
	v_mfma_f32_16x16x32_bf16 v[98:101], v[50:53], v[198:201], v[96:99]
	v_exp_f32_e32 v198, v126
	v_exp_f32_e32 v199, v127
	v_mul_f32_e32 v70, 0xbfb8aa3b, v70
	s_waitcnt lgkmcnt(0)
; __device__ __forceinline__ float fsig2(float x) { return __builtin_amdgcn_rcpf(1.0f + __builtin_amdgcn_exp2f(-LOG2E * x)); }
; template <int PASS> __device__ __forceinline__ void lru_wave_item(LAS unsigned char* lds, LAS unsigned char* vw, int b, int c, int h, const MixP& p, int lane, float (&Hrun)[8], bool cont) {
;     ...
;         for (int n = 0; n < 8; ++n) {
;             const f32x4 aVn = __builtin_amdgcn_mfma_f32_16x16x32_bf16(af[n >> 1], idf[n & 1], (f32x4){0.f, 0.f, 0.f, 0.f}, 0, 0, 0);
;             float av[4], bxv[4];
; #pragma unroll
;             for (int j = 0; j < 4; ++j) {
;                 const float r = fsig2(aR[n][j] + pba[n]), ig = fsig2(aI[n][j] + pbx[n]);
;                 const float a = __builtin_amdgcn_exp2f(r * pk8[n]), mult = __builtin_amdgcn_sqrtf(fmaxf(1.0f - a * a, 0.f));
;                 av[j] = a; bxv[j] = mult * ig * aVn[j];
;             }
;             const float H0 = bxv[0], H1 = av[1] * H0 + bxv[1], H2 = av[2] * H1 + bxv[2], H3 = av[3] * H2 + bxv[3];
;             const float A0 = av[0], A1 = av[1] * A0, A2 = av[2] * A1, A3 = av[3] * A2;
;             float At[4], Ht[4];
; #pragma unroll
;             for (int q = 0; q < 4; ++q) { At[q] = __shfl(A3, fr + 16 * q); Ht[q] = __shfl(H3, fr + 16 * q); }
;             const float c0 = Hrun[n], c1 = At[0] * c0 + Ht[0], c2 = At[1] * c1 + Ht[1], c3 = At[2] * c2 + Ht[2], c4 = At[3] * c3 + Ht[3];
;             Hrun[n] = c4;
;             if (PASS == 1) Arun[n] *= (At[0] * At[1]) * (At[2] * At[3]);
	v_mfma_f32_16x16x32_bf16 v[94:97], v[50:53], v[202:205], v[138:141]
	v_fma_f32 v126, -v198, v198, 1.0
	v_fma_f32 v127, -v199, v199, 1.0
	v_max_f32_e32 v126, 0, v126
	v_max_f32_e32 v127, 0, v127
	v_sqrt_f32_e32 v126, v126
	v_sqrt_f32_e32 v127, v127
	v_and_or_b32 v138, v213, 64, v137
	v_lshlrev_b32_e32 v151, 2, v138
	v_mfma_f32_16x16x32_bf16 v[138:141], v[110:113], v[2:5], 0
	v_mul_f32_e64 v122, v122, v126
	v_mul_f32_e64 v123, v123, v127
	v_add_f32_e32 v126, v170, v128
	v_mul_f32_e32 v126, 0xbfb8aa3b, v126
	v_exp_f32_e32 v126, v126
	v_rcp_f32_e32 v128, v125
	s_nop 1
	v_pk_mul_f32 v[122:123], v[122:123], v[138:139]
	v_mfma_f32_16x16x32_bf16 v[110:113], v[110:113], v[6:9], 0
	v_add_f32_e32 v126, 1.0, v126
	v_rcp_f32_e32 v126, v126
	v_fmac_f32_e32 v123, v199, v122
	v_mul_f32_e32 v71, 0xbfb8aa3b, v71
	v_exp_f32_e32 v70, v70
	v_mul_f32_e32 v126, v176, v126
	v_exp_f32_e32 v127, v126
	v_add_f32_e32 v126, v170, v129
	v_mul_f32_e32 v126, 0xbfb8aa3b, v126
	v_exp_f32_e32 v126, v126
	v_fma_f32 v122, -v127, v127, 1.0
	v_max_f32_e32 v122, 0, v122
	v_exp_f32_e32 v71, v71
	v_add_f32_e32 v126, 1.0, v126
	v_rcp_f32_e32 v126, v126
	v_add_f32_e32 v70, 1.0, v70
	v_add_f32_e32 v71, 1.0, v71
	v_rcp_f32_e32 v70, v70
	v_mul_f32_e32 v125, v176, v126
	v_sqrt_f32_e32 v126, v122
	v_exp_f32_e32 v139, v125
	v_mov_b32_e32 v125, v123
	v_rcp_f32_e32 v71, v71
	v_pk_mul_f32 v[122:123], v[124:125], v[126:127]
	v_exp_f32_e32 v124, v119
	v_fmac_f32_e32 v123, v122, v140
	v_fma_f32 v122, -v139, v139, 1.0
	v_max_f32_e32 v122, 0, v122
	v_sqrt_f32_e32 v138, v122
	v_mul_f32_e32 v122, v199, v198
	v_mul_f32_e32 v122, v127, v122
	v_mul_f32_e32 v122, v139, v122
	v_mov_b32_e32 v129, v123
	ds_bpermute_b32 v123, v151, v122
	ds_bpermute_b32 v127, v151, v122 offset:64
	ds_bpermute_b32 v199, v151, v122 offset:128
	ds_bpermute_b32 v203, v151, v122 offset:192
	v_exp_f32_e32 v122, v118
	v_fma_f32 v119, -v124, v124, 1.0
	v_max_f32_e32 v119, 0, v119
	v_sqrt_f32_e32 v119, v119
	v_fma_f32 v118, -v122, v122, 1.0
	v_max_f32_e32 v118, 0, v118
	v_sqrt_f32_e32 v118, v118
	v_pk_mul_f32 v[204:205], v[128:129], v[138:139]
	v_add_f32_e32 v66, v187, v66
	v_fmac_f32_e32 v205, v204, v141
	v_pk_mul_f32 v[114:115], v[114:115], v[118:119]
	ds_bpermute_b32 v125, v151, v205
	v_pk_mul_f32 v[110:111], v[114:115], v[110:111]
	v_add_f32_e32 v114, v171, v120
	v_mul_f32_e32 v114, 0xbfb8aa3b, v114
	v_exp_f32_e32 v114, v114
	v_fmac_f32_e32 v111, v124, v110
	ds_bpermute_b32 v129, v151, v205 offset:64
	ds_bpermute_b32 v201, v151, v205 offset:128
	v_add_f32_e32 v114, 1.0, v114
	v_rcp_f32_e32 v115, v114
	v_add_f32_e32 v114, v175, v116
	v_mul_f32_e32 v114, 0xbfb8aa3b, v114
	v_exp_f32_e32 v114, v114
	v_mul_f32_e32 v115, v177, v115
	v_exp_f32_e32 v119, v115
	v_add_f32_e32 v115, v171, v121
	v_mul_f32_e32 v115, 0xbfb8aa3b, v115
	v_exp_f32_e32 v115, v115
	v_fma_f32 v110, -v119, v119, 1.0
	v_add_f32_e32 v114, 1.0, v114
	v_max_f32_e32 v110, 0, v110
	v_add_f32_e32 v115, 1.0, v115
	v_rcp_f32_e32 v115, v115
	v_rcp_f32_e32 v114, v114
	v_sqrt_f32_e32 v118, v110
	v_add_f32_e32 v116, v175, v117
	v_mul_f32_e32 v115, v177, v115
	v_exp_f32_e32 v121, v115
	v_mov_b32_e32 v115, v111
	v_pk_mul_f32 v[110:111], v[114:115], v[118:119]
	v_exp_f32_e32 v114, v106
	v_exp_f32_e32 v115, v107
	v_mul_f32_e32 v116, 0xbfb8aa3b, v116
	v_exp_f32_e32 v116, v116
	v_fma_f32 v106, -v114, v114, 1.0
	v_fma_f32 v107, -v115, v115, 1.0
	v_max_f32_e32 v106, 0, v106
	v_max_f32_e32 v107, 0, v107
	v_sqrt_f32_e32 v106, v106
	v_sqrt_f32_e32 v107, v107
	v_fmac_f32_e32 v111, v110, v112
	v_fma_f32 v110, -v121, v121, 1.0
	v_add_f32_e32 v116, 1.0, v116
	v_max_f32_e32 v110, 0, v110
	v_rcp_f32_e32 v116, v116
	v_sqrt_f32_e32 v120, v110
	v_pk_mul_f32 v[102:103], v[102:103], v[106:107]
	v_add_f32_e32 v106, v178, v108
	v_mul_f32_e32 v106, 0xbfb8aa3b, v106
	v_mov_b32_e32 v117, v111
	v_exp_f32_e32 v106, v106
	v_pk_mul_f32 v[110:111], v[116:117], v[120:121]
	ds_bpermute_b32 v205, v151, v205 offset:192
	v_fmac_f32_e32 v111, v110, v113
	v_mul_f32_e32 v110, v124, v122
	v_mul_f32_e32 v110, v119, v110
	v_mul_f32_e32 v110, v121, v110
	v_add_f32_e32 v106, 1.0, v106
	ds_bpermute_b32 v122, v151, v110
	ds_bpermute_b32 v126, v151, v110 offset:64
	ds_bpermute_b32 v198, v151, v110 offset:128
	ds_bpermute_b32 v202, v151, v110 offset:192
	v_rcp_f32_e32 v106, v106
	ds_bpermute_b32 v124, v151, v111
	ds_bpermute_b32 v128, v151, v111 offset:64
	ds_bpermute_b32 v200, v151, v111 offset:128
	ds_bpermute_b32 v204, v151, v111 offset:192
	v_mul_f32_e32 v106, v182, v106
	s_waitcnt lgkmcnt(6)
	v_pk_mul_f32 v[110:111], v[122:123], v[126:127]
	s_waitcnt lgkmcnt(4)
	v_pk_mul_f32 v[112:113], v[198:199], v[202:203]
	v_exp_f32_e32 v107, v106
	v_add_f32_e32 v106, v178, v109
	v_pk_mul_f32 v[110:111], v[110:111], v[112:113]
	s_waitcnt lgkmcnt(3)
	v_pk_fma_f32 v[112:113], v[172:173], v[122:123], v[124:125]
	v_mul_f32_e32 v106, 0xbfb8aa3b, v106
	s_waitcnt lgkmcnt(2)
	v_pk_fma_f32 v[112:113], v[112:113], v[126:127], v[128:129]
	v_exp_f32_e32 v106, v106
	s_waitcnt lgkmcnt(1)
	v_pk_fma_f32 v[112:113], v[112:113], v[198:199], v[200:201]
	v_pk_mul_f32 v[162:163], v[162:163], v[110:111]
	s_waitcnt lgkmcnt(0)
; __device__ __forceinline__ float fsig2(float x) { return __builtin_amdgcn_rcpf(1.0f + __builtin_amdgcn_exp2f(-LOG2E * x)); }
; template <int PASS> __device__ __forceinline__ void lru_wave_item(LAS unsigned char* lds, LAS unsigned char* vw, int b, int c, int h, const MixP& p, int lane, float (&Hrun)[8], bool cont) {
;     ...
;         for (int n = 0; n < 8; ++n) {
;             const f32x4 aVn = __builtin_amdgcn_mfma_f32_16x16x32_bf16(af[n >> 1], idf[n & 1], (f32x4){0.f, 0.f, 0.f, 0.f}, 0, 0, 0);
;             float av[4], bxv[4];
; #pragma unroll
;             for (int j = 0; j < 4; ++j) {
;                 const float r = fsig2(aR[n][j] + pba[n]), ig = fsig2(aI[n][j] + pbx[n]);
;                 const float a = __builtin_amdgcn_exp2f(r * pk8[n]), mult = __builtin_amdgcn_sqrtf(fmaxf(1.0f - a * a, 0.f));
;                 av[j] = a; bxv[j] = mult * ig * aVn[j];
;             }
;             const float H0 = bxv[0], H1 = av[1] * H0 + bxv[1], H2 = av[2] * H1 + bxv[2], H3 = av[3] * H2 + bxv[3];
;             const float A0 = av[0], A1 = av[1] * A0, A2 = av[2] * A1, A3 = av[3] * A2;
;             float At[4], Ht[4];
; #pragma unroll
;             for (int q = 0; q < 4; ++q) { At[q] = __shfl(A3, fr + 16 * q); Ht[q] = __shfl(H3, fr + 16 * q); }
;             const float c0 = Hrun[n], c1 = At[0] * c0 + Ht[0], c2 = At[1] * c1 + Ht[1], c3 = At[2] * c2 + Ht[2], c4 = At[3] * c3 + Ht[3];
;             Hrun[n] = c4;
;             if (PASS == 1) Arun[n] *= (At[0] * At[1]) * (At[2] * At[3]);
	v_pk_fma_f32 v[172:173], v[112:113], v[202:203], v[204:205]
	v_mfma_f32_16x16x32_bf16 v[110:113], v[82:85], v[2:5], 0
	v_add_f32_e32 v106, 1.0, v106
	v_rcp_f32_e32 v106, v106
	v_rcp_f32_e32 v108, v105
	v_mfma_f32_16x16x32_bf16 v[82:85], v[82:85], v[6:9], 0
	v_mul_f32_e32 v70, v189, v70
	s_nop 2
	v_pk_mul_f32 v[102:103], v[102:103], v[110:111]
	v_mul_f32_e32 v105, v182, v106
	v_fmac_f32_e32 v103, v115, v102
	v_fma_f32 v102, -v107, v107, 1.0
	v_max_f32_e32 v102, 0, v102
	v_sqrt_f32_e32 v106, v102
	v_exp_f32_e32 v111, v105
	v_mov_b32_e32 v105, v103
	v_add_f32_e32 v67, v187, v67
	v_pk_mul_f32 v[102:103], v[104:105], v[106:107]
	v_mul_f32_e32 v71, v189, v71
	v_fmac_f32_e32 v103, v102, v112
	v_fma_f32 v102, -v111, v111, 1.0
	v_max_f32_e32 v102, 0, v102
	v_sqrt_f32_e32 v110, v102
	v_mov_b32_e32 v109, v103
	v_mul_f32_e32 v66, 0xbfb8aa3b, v66
	v_mul_f32_e32 v67, 0xbfb8aa3b, v67
	v_pk_mul_f32 v[102:103], v[108:109], v[110:111]
	v_exp_f32_e32 v66, v66
	v_fmac_f32_e32 v103, v102, v113
	v_mul_f32_e32 v102, v115, v114
	v_mul_f32_e32 v102, v107, v102
	v_mul_f32_e32 v105, v111, v102
	ds_bpermute_b32 v102, v151, v105
	ds_bpermute_b32 v104, v151, v103
	ds_bpermute_b32 v106, v151, v105 offset:64
	ds_bpermute_b32 v108, v151, v103 offset:64
	ds_bpermute_b32 v110, v151, v105 offset:128
	ds_bpermute_b32 v112, v151, v103 offset:128
	ds_bpermute_b32 v114, v151, v105 offset:192
	ds_bpermute_b32 v116, v151, v103 offset:192
	v_exp_f32_e32 v103, v90
	v_exp_f32_e32 v105, v91
	v_exp_f32_e32 v67, v67
	v_add_f32_e32 v66, 1.0, v66
	v_fma_f32 v90, -v103, v103, 1.0
	v_fma_f32 v91, -v105, v105, 1.0
	v_max_f32_e32 v90, 0, v90
	v_max_f32_e32 v91, 0, v91
	v_sqrt_f32_e32 v90, v90
	v_sqrt_f32_e32 v91, v91
	v_add_f32_e32 v67, 1.0, v67
	v_rcp_f32_e32 v66, v66
	v_rcp_f32_e32 v67, v67
	v_pk_mul_f32 v[86:87], v[86:87], v[90:91]
	v_add_f32_e32 v62, v190, v62
	v_pk_mul_f32 v[82:83], v[86:87], v[82:83]
	v_add_f32_e32 v86, v179, v92
	v_mul_f32_e32 v86, 0xbfb8aa3b, v86
	v_exp_f32_e32 v86, v86
	v_fmac_f32_e32 v83, v105, v82
	v_add_f32_e32 v63, v190, v63
	v_mul_f32_e32 v62, 0xbfb8aa3b, v62
	v_add_f32_e32 v86, 1.0, v86
	v_rcp_f32_e32 v87, v86
	v_add_f32_e32 v86, v181, v88
	v_mul_f32_e32 v86, 0xbfb8aa3b, v86
	v_exp_f32_e32 v86, v86
	v_mul_f32_e32 v87, v183, v87
	v_exp_f32_e32 v91, v87
	v_add_f32_e32 v87, v179, v93
	v_mul_f32_e32 v87, 0xbfb8aa3b, v87
	v_exp_f32_e32 v87, v87
	v_fma_f32 v82, -v91, v91, 1.0
	v_add_f32_e32 v86, 1.0, v86
	v_max_f32_e32 v82, 0, v82
	v_add_f32_e32 v87, 1.0, v87
	v_rcp_f32_e32 v87, v87
	v_rcp_f32_e32 v86, v86
	v_sqrt_f32_e32 v90, v82
	v_add_f32_e32 v88, v181, v89
	v_mul_f32_e32 v87, v183, v87
	v_exp_f32_e32 v93, v87
	v_mov_b32_e32 v87, v83
	v_pk_mul_f32 v[82:83], v[86:87], v[90:91]
	v_exp_f32_e32 v86, v78
	v_exp_f32_e32 v87, v79
	v_mul_f32_e32 v88, 0xbfb8aa3b, v88
	v_exp_f32_e32 v88, v88
	v_fma_f32 v78, -v86, v86, 1.0
	v_fma_f32 v79, -v87, v87, 1.0
	v_max_f32_e32 v78, 0, v78
	v_max_f32_e32 v79, 0, v79
	v_sqrt_f32_e32 v78, v78
	v_sqrt_f32_e32 v79, v79
	v_fmac_f32_e32 v83, v82, v84
	v_fma_f32 v82, -v93, v93, 1.0
	v_add_f32_e32 v88, 1.0, v88
	v_max_f32_e32 v82, 0, v82
	v_rcp_f32_e32 v88, v88
	v_sqrt_f32_e32 v92, v82
	v_pk_mul_f32 v[74:75], v[74:75], v[78:79]
	v_add_f32_e32 v78, v184, v80
	v_mul_f32_e32 v78, 0xbfb8aa3b, v78
	v_mov_b32_e32 v89, v83
	v_exp_f32_e32 v78, v78
	v_pk_mul_f32 v[82:83], v[88:89], v[92:93]
	v_rcp_f32_e32 v80, v77
	v_fmac_f32_e32 v83, v82, v85
	v_mul_f32_e32 v82, v105, v103
	v_mul_f32_e32 v82, v91, v82
	v_mul_f32_e32 v82, v93, v82
	v_add_f32_e32 v78, 1.0, v78
	ds_bpermute_b32 v103, v151, v82
	ds_bpermute_b32 v107, v151, v82 offset:64
	ds_bpermute_b32 v111, v151, v82 offset:128
	ds_bpermute_b32 v115, v151, v82 offset:192
	v_rcp_f32_e32 v78, v78
	ds_bpermute_b32 v105, v151, v83
	ds_bpermute_b32 v109, v151, v83 offset:64
	ds_bpermute_b32 v113, v151, v83 offset:128
	ds_bpermute_b32 v117, v151, v83 offset:192
	v_mul_f32_e32 v78, v188, v78
	s_waitcnt lgkmcnt(6)
	v_pk_mul_f32 v[82:83], v[102:103], v[106:107]
	s_waitcnt lgkmcnt(4)
	v_pk_mul_f32 v[84:85], v[110:111], v[114:115]
	v_exp_f32_e32 v79, v78
	v_add_f32_e32 v78, v184, v81
	v_pk_mul_f32 v[82:83], v[82:83], v[84:85]
	s_waitcnt lgkmcnt(3)
	v_pk_fma_f32 v[84:85], v[166:167], v[102:103], v[104:105]
	v_mul_f32_e32 v78, 0xbfb8aa3b, v78
	s_waitcnt lgkmcnt(2)
	v_pk_fma_f32 v[84:85], v[84:85], v[106:107], v[108:109]
	v_exp_f32_e32 v78, v78
	s_waitcnt lgkmcnt(1)
	v_pk_fma_f32 v[84:85], v[84:85], v[110:111], v[112:113]
	v_pk_mul_f32 v[168:169], v[168:169], v[82:83]
	s_waitcnt lgkmcnt(0)
; __device__ __forceinline__ float fsig2(float x) { return __builtin_amdgcn_rcpf(1.0f + __builtin_amdgcn_exp2f(-LOG2E * x)); }
; template <int PASS> __device__ __forceinline__ void lru_wave_item(LAS unsigned char* lds, LAS unsigned char* vw, int b, int c, int h, const MixP& p, int lane, float (&Hrun)[8], bool cont) {
;     ...
;         for (int n = 0; n < 8; ++n) {
;             const f32x4 aVn = __builtin_amdgcn_mfma_f32_16x16x32_bf16(af[n >> 1], idf[n & 1], (f32x4){0.f, 0.f, 0.f, 0.f}, 0, 0, 0);
;             float av[4], bxv[4];
; #pragma unroll
;             for (int j = 0; j < 4; ++j) {
;                 const float r = fsig2(aR[n][j] + pba[n]), ig = fsig2(aI[n][j] + pbx[n]);
;                 const float a = __builtin_amdgcn_exp2f(r * pk8[n]), mult = __builtin_amdgcn_sqrtf(fmaxf(1.0f - a * a, 0.f));
;                 av[j] = a; bxv[j] = mult * ig * aVn[j];
;             }
;             const float H0 = bxv[0], H1 = av[1] * H0 + bxv[1], H2 = av[2] * H1 + bxv[2], H3 = av[3] * H2 + bxv[3];
;             const float A0 = av[0], A1 = av[1] * A0, A2 = av[2] * A1, A3 = av[3] * A2;
;             float At[4], Ht[4];
; #pragma unroll
;             for (int q = 0; q < 4; ++q) { At[q] = __shfl(A3, fr + 16 * q); Ht[q] = __shfl(H3, fr + 16 * q); }
;             const float c0 = Hrun[n], c1 = At[0] * c0 + Ht[0], c2 = At[1] * c1 + Ht[1], c3 = At[2] * c2 + Ht[2], c4 = At[3] * c3 + Ht[3];
;             Hrun[n] = c4;
;             if (PASS == 1) Arun[n] *= (At[0] * At[1]) * (At[2] * At[3]);
	v_pk_fma_f32 v[166:167], v[84:85], v[114:115], v[116:117]
	v_mfma_f32_16x16x32_bf16 v[82:85], v[54:57], v[2:5], 0
	v_add_f32_e32 v78, 1.0, v78
	v_rcp_f32_e32 v78, v78
	v_mul_f32_e32 v63, 0xbfb8aa3b, v63
	v_mfma_f32_16x16x32_bf16 v[54:57], v[54:57], v[6:9], 0
	v_exp_f32_e32 v62, v62
	s_nop 2
	v_pk_mul_f32 v[74:75], v[74:75], v[82:83]
	v_mul_f32_e32 v77, v188, v78
	v_fmac_f32_e32 v75, v87, v74
	v_fma_f32 v74, -v79, v79, 1.0
	v_max_f32_e32 v74, 0, v74
	v_sqrt_f32_e32 v78, v74
	v_exp_f32_e32 v83, v77
	v_mov_b32_e32 v77, v75
	v_exp_f32_e32 v63, v63
	v_pk_mul_f32 v[74:75], v[76:77], v[78:79]
	v_add_f32_e32 v62, 1.0, v62
	v_fmac_f32_e32 v75, v74, v84
	v_fma_f32 v74, -v83, v83, 1.0
	v_max_f32_e32 v74, 0, v74
	v_sqrt_f32_e32 v82, v74
	v_mov_b32_e32 v81, v75
	v_add_f32_e32 v63, 1.0, v63
	v_rcp_f32_e32 v62, v62
	v_pk_mul_f32 v[74:75], v[80:81], v[82:83]
	v_rcp_f32_e32 v63, v63
	v_fmac_f32_e32 v75, v74, v85
	v_mul_f32_e32 v74, v87, v86
	v_mul_f32_e32 v74, v79, v74
	v_mul_f32_e32 v77, v83, v74
	ds_bpermute_b32 v74, v151, v77
	ds_bpermute_b32 v76, v151, v75
	ds_bpermute_b32 v78, v151, v77 offset:64
	ds_bpermute_b32 v80, v151, v75 offset:64
	ds_bpermute_b32 v82, v151, v77 offset:128
	ds_bpermute_b32 v84, v151, v75 offset:128
	ds_bpermute_b32 v86, v151, v77 offset:192
	ds_bpermute_b32 v88, v151, v75 offset:192
	v_exp_f32_e32 v75, v70
	v_exp_f32_e32 v77, v71
	v_add_f32_e32 v58, v192, v58
	v_mul_f32_e32 v62, v194, v62
	v_fma_f32 v70, -v75, v75, 1.0
	v_fma_f32 v71, -v77, v77, 1.0
	v_max_f32_e32 v70, 0, v70
	v_max_f32_e32 v71, 0, v71
	v_sqrt_f32_e32 v70, v70
	v_sqrt_f32_e32 v71, v71
	v_add_f32_e32 v59, v192, v59
	v_mul_f32_e32 v63, v194, v63
	v_mul_f32_e32 v58, 0xbfb8aa3b, v58
	v_pk_mul_f32 v[66:67], v[66:67], v[70:71]
	v_mul_f32_e32 v59, 0xbfb8aa3b, v59
	v_pk_mul_f32 v[54:55], v[66:67], v[54:55]
	v_add_f32_e32 v66, v185, v72
	v_mul_f32_e32 v66, 0xbfb8aa3b, v66
	v_exp_f32_e32 v66, v66
	v_fmac_f32_e32 v55, v77, v54
	v_exp_f32_e32 v58, v58
	v_exp_f32_e32 v59, v59
	v_add_f32_e32 v66, 1.0, v66
	v_rcp_f32_e32 v67, v66
	v_add_f32_e32 v66, v187, v68
	v_mul_f32_e32 v66, 0xbfb8aa3b, v66
	v_exp_f32_e32 v66, v66
	v_mul_f32_e32 v67, v189, v67
	v_exp_f32_e32 v71, v67
	v_add_f32_e32 v67, v185, v73
	v_mul_f32_e32 v67, 0xbfb8aa3b, v67
	v_exp_f32_e32 v67, v67
	v_fma_f32 v54, -v71, v71, 1.0
	v_add_f32_e32 v66, 1.0, v66
	v_max_f32_e32 v54, 0, v54
	v_add_f32_e32 v67, 1.0, v67
	v_rcp_f32_e32 v67, v67
	v_rcp_f32_e32 v66, v66
	v_add_f32_e32 v68, v187, v69
	v_sqrt_f32_e32 v70, v54
	v_mul_f32_e32 v67, v189, v67
	v_mul_f32_e32 v68, 0xbfb8aa3b, v68
	v_exp_f32_e32 v73, v67
	v_exp_f32_e32 v68, v68
	v_mov_b32_e32 v67, v55
	v_pk_mul_f32 v[54:55], v[66:67], v[70:71]
	v_exp_f32_e32 v66, v62
	v_fmac_f32_e32 v55, v54, v56
	v_fma_f32 v54, -v73, v73, 1.0
	v_add_f32_e32 v68, 1.0, v68
	v_max_f32_e32 v54, 0, v54
	v_rcp_f32_e32 v68, v68
	v_sqrt_f32_e32 v72, v54
	v_mov_b32_e32 v69, v55
	v_exp_f32_e32 v67, v63
	v_fma_f32 v62, -v66, v66, 1.0
	v_pk_mul_f32 v[54:55], v[68:69], v[72:73]
	v_add_f32_e32 v58, 1.0, v58
	v_fmac_f32_e32 v55, v54, v57
	v_mul_f32_e32 v54, v77, v75
	v_mul_f32_e32 v54, v71, v54
	v_mul_f32_e32 v54, v73, v54
	ds_bpermute_b32 v75, v151, v54
	ds_bpermute_b32 v79, v151, v54 offset:64
	ds_bpermute_b32 v83, v151, v54 offset:128
	ds_bpermute_b32 v87, v151, v54 offset:192
	ds_bpermute_b32 v77, v151, v55
	ds_bpermute_b32 v81, v151, v55 offset:64
	ds_bpermute_b32 v85, v151, v55 offset:128
	ds_bpermute_b32 v89, v151, v55 offset:192
	s_waitcnt lgkmcnt(6)
	v_pk_mul_f32 v[54:55], v[74:75], v[78:79]
	s_waitcnt lgkmcnt(4)
	v_pk_mul_f32 v[56:57], v[82:83], v[86:87]
	v_fma_f32 v63, -v67, v67, 1.0
	v_pk_mul_f32 v[54:55], v[54:55], v[56:57]
	s_waitcnt lgkmcnt(3)
	v_pk_fma_f32 v[56:57], v[160:161], v[74:75], v[76:77]
	v_max_f32_e32 v62, 0, v62
	s_waitcnt lgkmcnt(2)
	v_pk_fma_f32 v[56:57], v[56:57], v[78:79], v[80:81]
	v_add_f32_e32 v59, 1.0, v59
	v_max_f32_e32 v63, 0, v63
	s_waitcnt lgkmcnt(1)
	v_pk_fma_f32 v[56:57], v[56:57], v[82:83], v[84:85]
	v_rcp_f32_e32 v58, v58
	v_sqrt_f32_e32 v62, v62
	v_rcp_f32_e32 v59, v59
	v_sqrt_f32_e32 v63, v63
	s_waitcnt lgkmcnt(0)
; __device__ __forceinline__ float fsig2(float x) { return __builtin_amdgcn_rcpf(1.0f + __builtin_amdgcn_exp2f(-LOG2E * x)); }
; template <int PASS> __device__ __forceinline__ void lru_wave_item(LAS unsigned char* lds, LAS unsigned char* vw, int b, int c, int h, const MixP& p, int lane, float (&Hrun)[8], bool cont) {
;     ...
;         for (int n = 0; n < 8; ++n) {
;             const f32x4 aVn = __builtin_amdgcn_mfma_f32_16x16x32_bf16(af[n >> 1], idf[n & 1], (f32x4){0.f, 0.f, 0.f, 0.f}, 0, 0, 0);
;             float av[4], bxv[4];
; #pragma unroll
;             for (int j = 0; j < 4; ++j) {
;                 const float r = fsig2(aR[n][j] + pba[n]), ig = fsig2(aI[n][j] + pbx[n]);
;                 const float a = __builtin_amdgcn_exp2f(r * pk8[n]), mult = __builtin_amdgcn_sqrtf(fmaxf(1.0f - a * a, 0.f));
;                 av[j] = a; bxv[j] = mult * ig * aVn[j];
;             }
;             const float H0 = bxv[0], H1 = av[1] * H0 + bxv[1], H2 = av[2] * H1 + bxv[2], H3 = av[3] * H2 + bxv[3];
;             const float A0 = av[0], A1 = av[1] * A0, A2 = av[2] * A1, A3 = av[3] * A2;
;             float At[4], Ht[4];
; #pragma unroll
;             for (int q = 0; q < 4; ++q) { At[q] = __shfl(A3, fr + 16 * q); Ht[q] = __shfl(H3, fr + 16 * q); }
;             const float c0 = Hrun[n], c1 = At[0] * c0 + Ht[0], c2 = At[1] * c1 + Ht[1], c3 = At[2] * c2 + Ht[2], c4 = At[3] * c3 + Ht[3];
;             Hrun[n] = c4;
;             if (PASS == 1) Arun[n] *= (At[0] * At[1]) * (At[2] * At[3]);
;     ...
;     if (PASS == 1 && fq == 0) {
; #pragma unroll
;         for (int n = 0; n < 8; ++n) *(f32x2*)(p.summ + (((size_t)b * NCH + c) * LW + h * 128 + 16 * n + fr) * 2) = (f32x2){Arun[n], Hrun[n]};
;     }
	v_pk_fma_f32 v[160:161], v[56:57], v[86:87], v[88:89]
	v_pk_mul_f32 v[164:165], v[164:165], v[54:55]
	v_mfma_f32_16x16x32_bf16 v[54:57], v[50:53], v[2:5], 0
	v_mul_f32_e64 v58, v58, v62
	v_mul_f32_e64 v59, v59, v63
	v_mfma_f32_16x16x32_bf16 v[50:53], v[50:53], v[6:9], 0
	s_nop 4
	v_mul_f32_e64 v54, v58, v54
	v_mul_f32_e64 v55, v59, v55
	v_add_f32_e32 v58, v190, v64
	v_mul_f32_e32 v58, 0xbfb8aa3b, v58
	v_exp_f32_e32 v58, v58
	v_fmac_f32_e32 v55, v67, v54
	v_add_f32_e32 v58, 1.0, v58
	v_rcp_f32_e32 v59, v58
	v_add_f32_e32 v58, v192, v60
	v_mul_f32_e32 v58, 0xbfb8aa3b, v58
	v_exp_f32_e32 v58, v58
	v_mul_f32_e32 v59, v194, v59
	v_exp_f32_e32 v63, v59
	v_add_f32_e32 v59, v190, v65
	v_mul_f32_e32 v59, 0xbfb8aa3b, v59
	v_exp_f32_e32 v59, v59
	v_fma_f32 v54, -v63, v63, 1.0
	v_add_f32_e32 v58, 1.0, v58
	v_max_f32_e32 v54, 0, v54
	v_add_f32_e32 v59, 1.0, v59
	v_rcp_f32_e32 v59, v59
	v_rcp_f32_e32 v58, v58
	v_add_f32_e32 v60, v192, v61
	v_sqrt_f32_e32 v62, v54
	v_mul_f32_e32 v59, v194, v59
	v_mul_f32_e32 v60, 0xbfb8aa3b, v60
	v_exp_f32_e32 v65, v59
	v_exp_f32_e32 v60, v60
	v_mov_b32_e32 v59, v55
	v_pk_mul_f32 v[54:55], v[58:59], v[62:63]
	v_add_f32_e32 v59, v193, v95
	v_fmac_f32_e32 v55, v54, v56
	v_fma_f32 v54, -v65, v65, 1.0
	v_add_f32_e32 v60, 1.0, v60
	v_max_f32_e32 v54, 0, v54
	v_rcp_f32_e32 v60, v60
	v_sqrt_f32_e32 v64, v54
	v_mov_b32_e32 v61, v55
	v_mul_f32_e32 v59, 0xbfb8aa3b, v59
	v_exp_f32_e32 v59, v59
	v_pk_mul_f32 v[54:55], v[60:61], v[64:65]
	v_add_f32_e32 v61, v193, v96
	v_fmac_f32_e32 v55, v54, v57
	ds_bpermute_b32 v56, v151, v55
	ds_bpermute_b32 v60, v151, v55 offset:64
	ds_bpermute_b32 v64, v151, v55 offset:128
	ds_bpermute_b32 v68, v151, v55 offset:192
	v_add_f32_e32 v55, v191, v98
	v_mul_f32_e32 v55, 0xbfb8aa3b, v55
	v_exp_f32_e32 v55, v55
	v_mul_f32_e32 v54, v67, v66
	v_mul_f32_e32 v54, v63, v54
	v_mul_f32_e32 v57, v65, v54
	v_add_f32_e32 v55, 1.0, v55
	v_rcp_f32_e32 v55, v55
	ds_bpermute_b32 v54, v151, v57
	ds_bpermute_b32 v58, v151, v57 offset:64
	ds_bpermute_b32 v62, v151, v57 offset:128
	ds_bpermute_b32 v66, v151, v57 offset:192
	v_add_f32_e32 v57, v193, v94
	v_mul_f32_e32 v57, 0xbfb8aa3b, v57
	v_exp_f32_e32 v57, v57
	v_mul_f32_e32 v55, v195, v55
	v_exp_f32_e32 v55, v55
	v_add_f32_e32 v59, 1.0, v59
	v_add_f32_e32 v57, 1.0, v57
	v_rcp_f32_e32 v70, v57
	v_fma_f32 v57, -v55, v55, 1.0
	v_max_f32_e32 v57, 0, v57
	v_sqrt_f32_e32 v72, v57
	v_add_f32_e32 v57, v191, v99
	v_mul_f32_e32 v57, 0xbfb8aa3b, v57
	v_exp_f32_e32 v57, v57
	v_rcp_f32_e32 v71, v59
	v_mul_f32_e32 v61, 0xbfb8aa3b, v61
	v_exp_f32_e32 v61, v61
	v_add_f32_e32 v57, 1.0, v57
	v_rcp_f32_e32 v57, v57
	v_add_f32_e32 v61, 1.0, v61
	v_mul_f32_e32 v57, v195, v57
	v_exp_f32_e32 v57, v57
	s_nop 0
	v_fma_f32 v59, -v57, v57, 1.0
	v_max_f32_e32 v59, 0, v59
	v_sqrt_f32_e32 v73, v59
	v_add_f32_e32 v59, v191, v100
	v_mul_f32_e32 v59, 0xbfb8aa3b, v59
	v_exp_f32_e32 v59, v59
	v_pk_mul_f32 v[70:71], v[70:71], v[72:73]
	v_add_f32_e32 v59, 1.0, v59
	v_rcp_f32_e32 v59, v59
	v_pk_mul_f32 v[50:51], v[70:71], v[50:51]
	v_rcp_f32_e32 v70, v61
	v_fmac_f32_e32 v51, v57, v50
	v_mul_f32_e32 v59, v195, v59
	v_exp_f32_e32 v73, v59
	v_add_f32_e32 v59, v191, v101
	v_mul_f32_e32 v59, 0xbfb8aa3b, v59
	v_exp_f32_e32 v59, v59
	v_fma_f32 v50, -v73, v73, 1.0
	v_max_f32_e32 v50, 0, v50
	v_add_f32_e32 v61, v193, v97
	v_add_f32_e32 v59, 1.0, v59
	v_rcp_f32_e32 v59, v59
	v_sqrt_f32_e32 v72, v50
	v_mul_f32_e32 v61, 0xbfb8aa3b, v61
	v_exp_f32_e32 v61, v61
	v_mul_f32_e32 v59, v195, v59
	v_exp_f32_e32 v77, v59
	v_mov_b32_e32 v71, v51
	v_pk_mul_f32 v[50:51], v[70:71], v[72:73]
	v_add_f32_e32 v61, 1.0, v61
	v_fmac_f32_e32 v51, v50, v52
	v_fma_f32 v50, -v77, v77, 1.0
	v_max_f32_e32 v50, 0, v50
	v_rcp_f32_e32 v74, v61
	v_sqrt_f32_e32 v76, v50
	v_mov_b32_e32 v75, v51
	v_pk_mul_f32 v[50:51], v[74:75], v[76:77]
	s_nop 0
	v_fmac_f32_e32 v51, v50, v53
	v_mul_f32_e32 v50, v57, v55
	v_mul_f32_e32 v50, v73, v50
	v_mul_f32_e32 v50, v77, v50
	ds_bpermute_b32 v55, v151, v50
	ds_bpermute_b32 v59, v151, v50 offset:64
	ds_bpermute_b32 v63, v151, v50 offset:128
	ds_bpermute_b32 v67, v151, v50 offset:192
	ds_bpermute_b32 v57, v151, v51
	ds_bpermute_b32 v61, v151, v51 offset:64
	ds_bpermute_b32 v65, v151, v51 offset:128
	ds_bpermute_b32 v69, v151, v51 offset:192
	s_waitcnt lgkmcnt(6)
	v_pk_mul_f32 v[50:51], v[54:55], v[58:59]
	s_waitcnt lgkmcnt(4)
	v_pk_mul_f32 v[52:53], v[62:63], v[66:67]
	s_nop 0
	v_pk_mul_f32 v[50:51], v[50:51], v[52:53]
	s_waitcnt lgkmcnt(3)
	v_pk_fma_f32 v[52:53], v[156:157], v[54:55], v[56:57]
	v_pk_mul_f32 v[158:159], v[158:159], v[50:51]
	s_waitcnt lgkmcnt(2)
	v_pk_fma_f32 v[52:53], v[52:53], v[58:59], v[60:61]
	s_waitcnt lgkmcnt(1)
	v_pk_fma_f32 v[52:53], v[52:53], v[62:63], v[64:65]
	s_waitcnt lgkmcnt(0)
	v_pk_fma_f32 v[156:157], v[52:53], v[66:67], v[68:69]
	s_cbranch_vccz .LBB0_668
	s_and_saveexec_b64 s[28:29], s[4:5]
	s_cbranch_execz .LBB0_666
	s_ashr_i32 s59, s58, 31
	s_lshl_b64 s[16:17], s[58:59], 6
	s_ashr_i32 s2, s11, 31
	s_add_u32 s3, s16, s11
	s_addc_u32 s2, s17, s2
	s_mulk_i32 s2, 0x500
	v_mad_u64_u32 v[10:11], s[16:17], s3, v217, v[152:153]
	v_add_u32_e32 v11, s2, v11
	v_mov_b32_e32 v12, v163
	v_mov_b32_e32 v13, v173
	v_lshl_add_u64 v[10:11], v[10:11], 3, s[94:95]
	global_store_dwordx2 v[10:11], v[12:13], off sc1
	v_mov_b32_e32 v12, v168
	v_mov_b32_e32 v13, v166
	global_store_dwordx2 v[10:11], v[12:13], off offset:256 sc1
	v_mov_b32_e32 v12, v164
	v_mov_b32_e32 v13, v160
	v_mov_b32_e32 v163, v172
	v_mov_b32_e32 v166, v169
	global_store_dwordx2 v[10:11], v[12:13], off offset:512 sc1
	v_mov_b32_e32 v160, v165
	v_mov_b32_e32 v12, v158
	v_mov_b32_e32 v13, v156
	v_mov_b32_e32 v156, v159
	global_store_dwordx2 v[10:11], v[162:163], off offset:128 sc1
	global_store_dwordx2 v[10:11], v[166:167], off offset:384 sc1
	global_store_dwordx2 v[10:11], v[160:161], off offset:640 sc1
	global_store_dwordx2 v[10:11], v[12:13], off offset:768 sc1
	global_store_dwordx2 v[10:11], v[156:157], off offset:896 sc1
	s_branch .LBB0_666

; #define LAS __attribute__((address_space(3)))
; __device__ __forceinline__ float bflo(unsigned w) { return __uint_as_float(w << 16); }
; __device__ __forceinline__ float bfhi(unsigned w) { return __uint_as_float(w & 0xffff0000u); }
; template <int PASS> __device__ __forceinline__ void lru_wave_item(LAS unsigned char* lds, LAS unsigned char* vw, int b, int c, int h, const MixP& p, int lane, float (&Hrun)[8], bool cont) {
;     ...
;     for (int st = 0; st < CT / 16; ++st) {
;         const int s0 = c * CT + 16 * st;
;         u32x4 ur[7];
;         {
;             const int sb = s0 + 4 * fq - 3;
; #pragma unroll
;             for (int r = 0; r < 7; ++r) ur[r] = *(const u32x4*)(ub + (size_t)max(sb + r, 0) * P1W);
;         }
;         if (s0 == 0 && fq == 0) {
; #pragma unroll
;             for (int r = 0; r < 3; ++r) ur[r] = (u32x4){0u, 0u, 0u, 0u};
;         }
; #pragma unroll
;         for (int jj = 0; jj < 4; ++jj) {
;             f32x2 o[4] = {bv[0], bv[1], bv[2], bv[3]};
; #pragma unroll
;             for (int k = 0; k < 4; ++k) { const u32x4 uk = ur[jj + k];
;                 o[0] = wv[k][0] * (f32x2){bflo(uk.x), bfhi(uk.x)} + o[0]; o[1] = wv[k][1] * (f32x2){bflo(uk.y), bfhi(uk.y)} + o[1];
;                 o[2] = wv[k][2] * (f32x2){bflo(uk.z), bfhi(uk.z)} + o[2]; o[3] = wv[k][3] * (f32x2){bflo(uk.w), bfhi(uk.w)} + o[3]; }
;     ...
;                 const int t = fq + 4 * i; const size_t row = (size_t)(row0 + 16 * st + t);
;                 const u32x4 hh = *(const LAS u32x4*)(vw + t * WROW + cg * 16);
;                 const u32x4 g = *(const u32x4*)(p.P2 + row * P2W + h * 128 + cg * 8);
.LBB0_818:
	s_or_b32 s22, s19, s11
	v_add_u32_e32 v0, s22, v224
	v_max_i32_e32 v2, 0, v0
	v_mad_u64_u32 v[2:3], s[20:21], v2, s82, v[182:183]
	global_load_dwordx4 v[74:77], v[2:3], off offset:1024
	v_max_i32_e32 v2, -1, v0
	v_add_u32_e32 v2, 1, v2
	v_mad_u64_u32 v[2:3], s[20:21], v2, s82, v[182:183]
	global_load_dwordx4 v[78:81], v[2:3], off offset:1024
	v_or_b32_e32 v2, 2, v0
	v_max_i32_e32 v2, 0, v2
	v_mad_u64_u32 v[2:3], s[20:21], v2, s82, v[182:183]
	global_load_dwordx4 v[82:85], v[2:3], off offset:1024
	v_or_b32_e32 v2, s22, v223
	v_max_i32_e32 v2, 0, v2
	v_mad_u64_u32 v[2:3], s[20:21], v2, s82, v[182:183]
	global_load_dwordx4 v[70:73], v[2:3], off offset:1024
	v_max_i32_e32 v2, -4, v0
	v_add_u32_e32 v2, 4, v2
	v_mad_u64_u32 v[2:3], s[20:21], v2, s82, v[182:183]
	global_load_dwordx4 v[66:69], v[2:3], off offset:1024
	v_max_i32_e32 v2, -5, v0
	v_add_u32_e32 v2, 5, v2
	v_mad_u64_u32 v[2:3], s[20:21], v2, s82, v[182:183]
	global_load_dwordx4 v[6:9], v[2:3], off offset:1024
	v_max_i32_e32 v0, -6, v0
	v_add_u32_e32 v0, 6, v0
	v_mad_u64_u32 v[2:3], s[20:21], v0, s82, v[182:183]
	global_load_dwordx4 v[2:5], v[2:3], off offset:1024
	s_cmp_eq_u32 s22, 0
	s_cselect_b64 s[20:21], -1, 0
	s_and_b64 s[20:21], s[20:21], s[4:5]
	s_or_b32 s19, s19, s18
	s_and_b64 vcc, exec, s[12:13]
	s_mov_b64 s[12:13], 0
	v_or_b32_e32 v96, s19, v203
	v_mad_i64_i32 v[240:241], s[98:99], v96, s83, v[152:153]
	global_load_dwordx4 v[240:243], v[240:241], off
	v_or_b32_e32 v96, s19, v225
	v_mad_i64_i32 v[244:245], s[98:99], v96, s83, v[152:153]
	global_load_dwordx4 v[244:247], v[244:245], off
	v_or_b32_e32 v96, s19, v226
	v_mad_i64_i32 v[248:249], s[98:99], v96, s83, v[152:153]
	global_load_dwordx4 v[248:251], v[248:249], off
	v_or_b32_e32 v96, s19, v227
	v_mad_i64_i32 v[206:207], s[98:99], v96, s83, v[152:153]
	global_load_dwordx2 v[210:211], v[206:207], off offset:8
	global_load_dwordx2 v[206:207], v[206:207], off
	s_add_i32 s100, s22, 16
	v_add_u32_e32 v96, s100, v224
	v_max_i32_e32 v97, 0, v96
	v_mad_u64_u32 v[98:99], s[98:99], v97, s82, v[182:183]
	global_load_dword v237, v[98:99], off offset:1024
	v_add_u32_e32 v97, 1, v96
	v_max_i32_e32 v97, 0, v97
	v_mad_u64_u32 v[98:99], s[98:99], v97, s82, v[182:183]
	global_load_dword v237, v[98:99], off offset:1024
	v_add_u32_e32 v97, 2, v96
	v_max_i32_e32 v97, 0, v97
	v_mad_u64_u32 v[98:99], s[98:99], v97, s82, v[182:183]
	global_load_dword v237, v[98:99], off offset:1024
	v_add_u32_e32 v97, 3, v96
	v_max_i32_e32 v97, 0, v97
	v_mad_u64_u32 v[98:99], s[98:99], v97, s82, v[182:183]
	global_load_dword v237, v[98:99], off offset:1024
	v_add_u32_e32 v97, 4, v96
	v_max_i32_e32 v97, 0, v97
	v_mad_u64_u32 v[98:99], s[98:99], v97, s82, v[182:183]
	global_load_dword v237, v[98:99], off offset:1024
	v_add_u32_e32 v97, 5, v96
	v_max_i32_e32 v97, 0, v97
	v_mad_u64_u32 v[98:99], s[98:99], v97, s82, v[182:183]
	global_load_dword v237, v[98:99], off offset:1024
	v_add_u32_e32 v97, 6, v96
	v_max_i32_e32 v97, 0, v97
	v_mad_u64_u32 v[98:99], s[98:99], v97, s82, v[182:183]
	global_load_dword v237, v[98:99], off offset:1024
	s_waitcnt vmcnt(18)
	v_cndmask_b32_e64 v0, v77, 0, s[20:21]
	v_cndmask_b32_e64 v77, v75, 0, s[20:21]
	v_cndmask_b32_e64 v75, v74, 0, s[20:21]
	v_cndmask_b32_e64 v86, v76, 0, s[20:21]
	v_lshlrev_b32_e32 v74, 16, v75
	s_waitcnt vmcnt(17)
	v_cndmask_b32_e64 v89, v79, 0, s[20:21]
	v_cndmask_b32_e64 v91, v78, 0, s[20:21]
	v_and_b32_e32 v75, 0xffff0000, v75
	v_lshlrev_b32_e32 v76, 16, v77
	v_and_b32_e32 v77, 0xffff0000, v77
	v_cndmask_b32_e64 v88, v81, 0, s[20:21]
	v_cndmask_b32_e64 v87, v80, 0, s[20:21]
	s_waitcnt vmcnt(16)
	v_cndmask_b32_e64 v102, v83, 0, s[20:21]
	v_cndmask_b32_e64 v98, v82, 0, s[20:21]
	s_waitcnt lgkmcnt(13)
	v_pk_fma_f32 v[74:75], v[26:27], v[74:75], v[58:59]
	v_pk_fma_f32 v[76:77], v[28:29], v[76:77], v[60:61]
	v_lshlrev_b32_e32 v78, 16, v86
	v_and_b32_e32 v79, 0xffff0000, v86
	v_lshlrev_b32_e32 v80, 16, v0
	v_and_b32_e32 v81, 0xffff0000, v0
	v_lshlrev_b32_e32 v90, 16, v91
	v_and_b32_e32 v91, 0xffff0000, v91
	v_lshlrev_b32_e32 v92, 16, v89
	v_and_b32_e32 v93, 0xffff0000, v89
	v_cndmask_b32_e64 v100, v85, 0, s[20:21]
	v_cndmask_b32_e64 v101, v84, 0, s[20:21]
	s_waitcnt lgkmcnt(12)
	v_pk_fma_f32 v[78:79], v[30:31], v[78:79], v[62:63]
	v_pk_fma_f32 v[80:81], v[32:33], v[80:81], v[64:65]
	v_pk_fma_f32 v[82:83], v[34:35], v[90:91], v[74:75]
	v_pk_fma_f32 v[84:85], v[36:37], v[92:93], v[76:77]
	v_lshlrev_b32_e32 v94, 16, v87
	v_and_b32_e32 v95, 0xffff0000, v87
	v_lshlrev_b32_e32 v96, 16, v88
	v_and_b32_e32 v97, 0xffff0000, v88
	v_lshlrev_b32_e32 v74, 16, v98
	v_and_b32_e32 v75, 0xffff0000, v98
	v_lshlrev_b32_e32 v76, 16, v102
	v_and_b32_e32 v77, 0xffff0000, v102
	v_pk_fma_f32 v[86:87], v[38:39], v[94:95], v[78:79]
	v_pk_fma_f32 v[88:89], v[40:41], v[96:97], v[80:81]
	v_pk_fma_f32 v[98:99], v[42:43], v[74:75], v[82:83]
	v_pk_fma_f32 v[84:85], v[44:45], v[76:77], v[84:85]
	v_lshlrev_b32_e32 v78, 16, v101
	v_and_b32_e32 v79, 0xffff0000, v101
	v_lshlrev_b32_e32 v80, 16, v100
	v_and_b32_e32 v81, 0xffff0000, v100
	s_waitcnt vmcnt(15)
	v_lshlrev_b32_e32 v82, 16, v70
	v_and_b32_e32 v83, 0xffff0000, v70
	v_lshlrev_b32_e32 v70, 16, v71
	v_and_b32_e32 v71, 0xffff0000, v71
	v_pk_fma_f32 v[86:87], v[46:47], v[78:79], v[86:87]
	v_pk_fma_f32 v[88:89], v[48:49], v[80:81], v[88:89]
	v_pk_fma_f32 v[100:101], v[52:53], v[70:71], v[84:85]
	v_lshlrev_b32_e32 v84, 16, v72
	v_and_b32_e32 v85, 0xffff0000, v72
	v_lshlrev_b32_e32 v72, 16, v73
	v_and_b32_e32 v73, 0xffff0000, v73
	v_pk_fma_f32 v[98:99], v[50:51], v[82:83], v[98:99]
	v_pk_fma_f32 v[102:103], v[54:55], v[84:85], v[86:87]
	v_pk_fma_f32 v[104:105], v[56:57], v[72:73], v[88:89]
	v_cvt_pk_bf16_f32 v86, v98, v99
	v_cvt_pk_bf16_f32 v87, v100, v101
	v_cvt_pk_bf16_f32 v88, v102, v103
	s_waitcnt vmcnt(14)
; #define LAS __attribute__((address_space(3)))
; __device__ __forceinline__ unsigned cvt_pk_bf16(float lo, float hi) { unsigned r; asm volatile("v_cvt_pk_bf16_f32 %0, %1, %2" : "=v"(r) : "v"(lo), "v"(hi)); return r; }
; __device__ __forceinline__ float bflo(unsigned w) { return __uint_as_float(w << 16); }
; __device__ __forceinline__ float bfhi(unsigned w) { return __uint_as_float(w & 0xffff0000u); }
; template <int PASS> __device__ __forceinline__ void lru_wave_item(LAS unsigned char* lds, LAS unsigned char* vw, int b, int c, int h, const MixP& p, int lane, float (&Hrun)[8], bool cont) {
;     ...
;         for (int jj = 0; jj < 4; ++jj) {
;             f32x2 o[4] = {bv[0], bv[1], bv[2], bv[3]};
; #pragma unroll
;             for (int k = 0; k < 4; ++k) { const u32x4 uk = ur[jj + k];
;                 o[0] = wv[k][0] * (f32x2){bflo(uk.x), bfhi(uk.x)} + o[0]; o[1] = wv[k][1] * (f32x2){bflo(uk.y), bfhi(uk.y)} + o[1];
;                 o[2] = wv[k][2] * (f32x2){bflo(uk.z), bfhi(uk.z)} + o[2]; o[3] = wv[k][3] * (f32x2){bflo(uk.w), bfhi(uk.w)} + o[3]; }
;             { u32x4 w; w.x = cvt_pk_bf16(o[0].x, o[0].y); w.y = cvt_pk_bf16(o[1].x, o[1].y); w.z = cvt_pk_bf16(o[2].x, o[2].y); w.w = cvt_pk_bf16(o[3].x, o[3].y);
;               *(LAS u32x4*)(vw + (4 * fq + jj) * WROW + cg * 16) = w; }
;         }
;         f32x4 aR[8], aI[8];
;         bf16x8 af[4];
;         {
; #pragma unroll
;             for (int kk = 0; kk < 4; ++kk) af[kk] = *(const LAS bf16x8*)(vw + fr * WROW + kk * 64 + fq * 16);
; #pragma unroll
;             for (int n = 0; n < 8; ++n) {
;                 aR[n] = (f32x4){0.f, 0.f, 0.f, 0.f}; aI[n] = (f32x4){0.f, 0.f, 0.f, 0.f};
; #pragma unroll
;                 for (int kk = 0; kk < 4; ++kk) {
;                     const bf16x8 ba = *(const LAS bf16x8*)(lds + WA_OFF + (16 * n + fr) * WROW + kk * 64 + fq * 16);
;                     const bf16x8 bx = *(const LAS bf16x8*)(lds + WX_OFF + (16 * n + fr) * WROW + kk * 64 + fq * 16);
;                     aR[n] = __builtin_amdgcn_mfma_f32_16x16x32_bf16(af[kk], ba, aR[n], 0, 0, 0);
;                     aI[n] = __builtin_amdgcn_mfma_f32_16x16x32_bf16(af[kk], bx, aI[n], 0, 0, 0);
;                 }
;             }
	v_lshlrev_b32_e32 v98, 16, v68
	v_cvt_pk_bf16_f32 v89, v104, v105
	ds_write_b128 v229, v[86:89]
	v_pk_fma_f32 v[86:87], v[26:27], v[90:91], v[58:59]
	v_pk_fma_f32 v[88:89], v[28:29], v[92:93], v[60:61]
	v_pk_fma_f32 v[90:91], v[30:31], v[94:95], v[62:63]
	v_pk_fma_f32 v[92:93], v[32:33], v[96:97], v[64:65]
	v_pk_fma_f32 v[86:87], v[34:35], v[74:75], v[86:87]
	v_pk_fma_f32 v[88:89], v[36:37], v[76:77], v[88:89]
	v_pk_fma_f32 v[90:91], v[38:39], v[78:79], v[90:91]
	v_pk_fma_f32 v[92:93], v[40:41], v[80:81], v[92:93]
	v_pk_fma_f32 v[86:87], v[42:43], v[82:83], v[86:87]
	v_pk_fma_f32 v[88:89], v[44:45], v[70:71], v[88:89]
	v_pk_fma_f32 v[90:91], v[46:47], v[84:85], v[90:91]
	v_pk_fma_f32 v[92:93], v[48:49], v[72:73], v[92:93]
	v_lshlrev_b32_e32 v94, 16, v66
	v_and_b32_e32 v95, 0xffff0000, v66
	v_lshlrev_b32_e32 v96, 16, v67
	v_and_b32_e32 v97, 0xffff0000, v67
	v_and_b32_e32 v99, 0xffff0000, v68
	v_lshlrev_b32_e32 v100, 16, v69
	v_and_b32_e32 v101, 0xffff0000, v69
	v_pk_fma_f32 v[86:87], v[50:51], v[94:95], v[86:87]
	v_pk_fma_f32 v[88:89], v[52:53], v[96:97], v[88:89]
	v_pk_fma_f32 v[90:91], v[54:55], v[98:99], v[90:91]
	v_pk_fma_f32 v[92:93], v[56:57], v[100:101], v[92:93]
	v_cvt_pk_bf16_f32 v66, v86, v87
	v_cvt_pk_bf16_f32 v67, v88, v89
	v_cvt_pk_bf16_f32 v68, v90, v91
	s_waitcnt vmcnt(13)
	v_lshlrev_b32_e32 v86, 16, v8
	v_cvt_pk_bf16_f32 v69, v92, v93
	ds_write_b128 v229, v[66:69] offset:272
	v_pk_fma_f32 v[66:67], v[26:27], v[74:75], v[58:59]
	v_pk_fma_f32 v[68:69], v[28:29], v[76:77], v[60:61]
	v_pk_fma_f32 v[74:75], v[30:31], v[78:79], v[62:63]
	v_pk_fma_f32 v[76:77], v[32:33], v[80:81], v[64:65]
	v_pk_fma_f32 v[66:67], v[34:35], v[82:83], v[66:67]
	v_pk_fma_f32 v[68:69], v[36:37], v[70:71], v[68:69]
	v_pk_fma_f32 v[74:75], v[38:39], v[84:85], v[74:75]
	v_pk_fma_f32 v[76:77], v[40:41], v[72:73], v[76:77]
	v_pk_fma_f32 v[66:67], v[42:43], v[94:95], v[66:67]
	v_pk_fma_f32 v[68:69], v[44:45], v[96:97], v[68:69]
	v_pk_fma_f32 v[74:75], v[46:47], v[98:99], v[74:75]
	v_pk_fma_f32 v[76:77], v[48:49], v[100:101], v[76:77]
	v_lshlrev_b32_e32 v78, 16, v6
	v_and_b32_e32 v79, 0xffff0000, v6
	v_lshlrev_b32_e32 v80, 16, v7
	v_and_b32_e32 v81, 0xffff0000, v7
	v_and_b32_e32 v87, 0xffff0000, v8
	v_lshlrev_b32_e32 v88, 16, v9
	v_and_b32_e32 v89, 0xffff0000, v9
	v_pk_fma_f32 v[66:67], v[50:51], v[78:79], v[66:67]
	v_pk_fma_f32 v[68:69], v[52:53], v[80:81], v[68:69]
	v_pk_fma_f32 v[74:75], v[54:55], v[86:87], v[74:75]
	v_pk_fma_f32 v[76:77], v[56:57], v[88:89], v[76:77]
	v_cvt_pk_bf16_f32 v6, v66, v67
	v_cvt_pk_bf16_f32 v7, v68, v69
	v_cvt_pk_bf16_f32 v8, v74, v75
	v_pk_fma_f32 v[66:67], v[30:31], v[84:85], v[62:63]
	v_cvt_pk_bf16_f32 v9, v76, v77
	ds_write_b128 v229, v[6:9] offset:544
	v_pk_fma_f32 v[6:7], v[26:27], v[82:83], v[58:59]
	v_pk_fma_f32 v[8:9], v[28:29], v[70:71], v[60:61]
	v_pk_fma_f32 v[68:69], v[32:33], v[72:73], v[64:65]
	v_pk_fma_f32 v[6:7], v[34:35], v[94:95], v[6:7]
	v_pk_fma_f32 v[8:9], v[36:37], v[96:97], v[8:9]
	v_pk_fma_f32 v[66:67], v[38:39], v[98:99], v[66:67]
	v_pk_fma_f32 v[68:69], v[40:41], v[100:101], v[68:69]
	v_pk_fma_f32 v[6:7], v[42:43], v[78:79], v[6:7]
	v_pk_fma_f32 v[8:9], v[44:45], v[80:81], v[8:9]
	v_pk_fma_f32 v[70:71], v[46:47], v[86:87], v[66:67]
	v_pk_fma_f32 v[66:67], v[48:49], v[88:89], v[68:69]
	s_waitcnt vmcnt(12)
	v_lshlrev_b32_e32 v68, 16, v2
	v_and_b32_e32 v69, 0xffff0000, v2
	v_lshlrev_b32_e32 v2, 16, v3
	v_and_b32_e32 v3, 0xffff0000, v3
	v_pk_fma_f32 v[6:7], v[50:51], v[68:69], v[6:7]
	v_pk_fma_f32 v[2:3], v[52:53], v[2:3], v[8:9]
	v_lshlrev_b32_e32 v8, 16, v4
	v_and_b32_e32 v9, 0xffff0000, v4
	v_lshlrev_b32_e32 v4, 16, v5
	v_and_b32_e32 v5, 0xffff0000, v5
	v_pk_fma_f32 v[8:9], v[54:55], v[8:9], v[70:71]
	v_pk_fma_f32 v[66:67], v[56:57], v[4:5], v[66:67]
	v_cvt_pk_bf16_f32 v4, v6, v7
	v_cvt_pk_bf16_f32 v5, v2, v3
	v_cvt_pk_bf16_f32 v6, v8, v9
	v_and_or_b32 v0, v213, 64, v202
	v_cvt_pk_bf16_f32 v7, v66, v67
	ds_write_b128 v229, v[4:7] offset:816
	ds_read_b128 v[118:121], v230
	ds_read_b128 v[90:93], v230 offset:64
	ds_read_b128 v[6:9], v230 offset:128
	ds_read_b128 v[2:5], v230 offset:192
	ds_read_b128 v[66:69], v231
	ds_read_b128 v[70:73], v231 offset:34816
	ds_read_b128 v[74:77], v231 offset:64
	ds_read_b128 v[78:81], v231 offset:34880
	s_waitcnt lgkmcnt(3)
	v_mfma_f32_16x16x32_bf16 v[66:69], v[118:121], v[66:69], 0
	v_lshlrev_b32_e32 v0, 2, v0
	s_waitcnt lgkmcnt(2)
	v_mfma_f32_16x16x32_bf16 v[70:73], v[118:121], v[70:73], 0
	s_waitcnt lgkmcnt(1)
	v_mfma_f32_16x16x32_bf16 v[66:69], v[90:93], v[74:77], v[66:69]
	s_waitcnt lgkmcnt(0)
	v_mfma_f32_16x16x32_bf16 v[70:73], v[90:93], v[78:81], v[70:73]
	ds_read_b128 v[74:77], v231 offset:128
	ds_read_b128 v[78:81], v231 offset:34944
	s_waitcnt lgkmcnt(1)
	v_mfma_f32_16x16x32_bf16 v[66:69], v[6:9], v[74:77], v[66:69]
	s_waitcnt lgkmcnt(0)
	v_mfma_f32_16x16x32_bf16 v[70:73], v[6:9], v[78:81], v[70:73]
	ds_read_b128 v[74:77], v231 offset:192
	ds_read_b128 v[78:81], v231 offset:35008
	s_waitcnt lgkmcnt(1)
	v_mfma_f32_16x16x32_bf16 v[134:137], v[2:5], v[74:77], v[66:69]
	s_waitcnt lgkmcnt(0)
	v_mfma_f32_16x16x32_bf16 v[130:133], v[2:5], v[78:81], v[70:73]
	s_nop 0
	ds_read_b128 v[66:69], v231 offset:4352
	s_nop 0
	ds_read_b128 v[70:73], v231 offset:39168
	ds_read_b128 v[74:77], v231 offset:4416
	ds_read_b128 v[78:81], v231 offset:39232
	v_add_f32_e32 v134, v158, v134
	s_waitcnt lgkmcnt(3)
	v_mfma_f32_16x16x32_bf16 v[66:69], v[118:121], v[66:69], 0
	v_add_f32_e32 v135, v158, v135
	v_mul_f32_e32 v134, 0xbfb8aa3b, v134
	v_mul_f32_e32 v135, 0xbfb8aa3b, v135
	s_waitcnt lgkmcnt(2)
	v_mfma_f32_16x16x32_bf16 v[70:73], v[118:121], v[70:73], 0
	v_exp_f32_e32 v134, v134
	v_exp_f32_e32 v135, v135
	v_add_f32_e32 v130, v160, v130
	s_waitcnt lgkmcnt(1)
; #define LAS __attribute__((address_space(3)))
; template <int PASS> __device__ __forceinline__ void lru_wave_item(LAS unsigned char* lds, LAS unsigned char* vw, int b, int c, int h, const MixP& p, int lane, float (&Hrun)[8], bool cont) {
;     ...
;             for (int kk = 0; kk < 4; ++kk) af[kk] = *(const LAS bf16x8*)(vw + fr * WROW + kk * 64 + fq * 16);
; #pragma unroll
;             for (int n = 0; n < 8; ++n) {
;                 aR[n] = (f32x4){0.f, 0.f, 0.f, 0.f}; aI[n] = (f32x4){0.f, 0.f, 0.f, 0.f};
; #pragma unroll
;                 for (int kk = 0; kk < 4; ++kk) {
;                     const bf16x8 ba = *(const LAS bf16x8*)(lds + WA_OFF + (16 * n + fr) * WROW + kk * 64 + fq * 16);
;                     const bf16x8 bx = *(const LAS bf16x8*)(lds + WX_OFF + (16 * n + fr) * WROW + kk * 64 + fq * 16);
;                     aR[n] = __builtin_amdgcn_mfma_f32_16x16x32_bf16(af[kk], ba, aR[n], 0, 0, 0);
;                     aI[n] = __builtin_amdgcn_mfma_f32_16x16x32_bf16(af[kk], bx, aI[n], 0, 0, 0);
;                 }
;             }
	v_mfma_f32_16x16x32_bf16 v[66:69], v[90:93], v[74:77], v[66:69]
	v_add_f32_e32 v134, 1.0, v134
	v_add_f32_e32 v135, 1.0, v135
	v_rcp_f32_e32 v134, v134
	s_waitcnt lgkmcnt(0)
	v_mfma_f32_16x16x32_bf16 v[70:73], v[90:93], v[78:81], v[70:73]
	ds_read_b128 v[74:77], v231 offset:4480
	ds_read_b128 v[78:81], v231 offset:39296
	v_rcp_f32_e32 v135, v135
	v_mul_f32_e32 v134, v162, v134
	s_waitcnt lgkmcnt(1)
	v_mfma_f32_16x16x32_bf16 v[66:69], v[6:9], v[74:77], v[66:69]
	v_add_f32_e32 v131, v160, v131
	v_mul_f32_e32 v135, v162, v135
	v_mul_f32_e32 v130, 0xbfb8aa3b, v130
	s_waitcnt lgkmcnt(0)
	v_mfma_f32_16x16x32_bf16 v[70:73], v[6:9], v[78:81], v[70:73]
	ds_read_b128 v[74:77], v231 offset:4544
	ds_read_b128 v[78:81], v231 offset:39360
	v_exp_f32_e32 v236, v134
	v_mul_f32_e32 v131, 0xbfb8aa3b, v131
	s_waitcnt lgkmcnt(1)
	v_mfma_f32_16x16x32_bf16 v[126:129], v[2:5], v[74:77], v[66:69]
	v_exp_f32_e32 v130, v130
	v_exp_f32_e32 v131, v131
	v_fma_f32 v134, -v236, v236, 1.0
	s_waitcnt lgkmcnt(0)
	v_mfma_f32_16x16x32_bf16 v[122:125], v[2:5], v[78:81], v[70:73]
	ds_read_b128 v[66:69], v231 offset:8704
	s_nop 1
	ds_read_b128 v[70:73], v231 offset:43520
	ds_read_b128 v[74:77], v231 offset:8768
	ds_read_b128 v[78:81], v231 offset:43584
	v_add_f32_e32 v130, 1.0, v130
	s_waitcnt lgkmcnt(3)
	v_mfma_f32_16x16x32_bf16 v[66:69], v[118:121], v[66:69], 0
	v_max_f32_e32 v134, 0, v134
	v_add_f32_e32 v131, 1.0, v131
	v_rcp_f32_e32 v130, v130
	s_waitcnt lgkmcnt(2)
	v_mfma_f32_16x16x32_bf16 v[70:73], v[118:121], v[70:73], 0
	v_sqrt_f32_e32 v134, v134
	v_rcp_f32_e32 v131, v131
	v_add_f32_e32 v133, v160, v133
	s_waitcnt lgkmcnt(1)
	v_mfma_f32_16x16x32_bf16 v[66:69], v[90:93], v[74:77], v[66:69]
	v_mul_f32_e32 v133, 0xbfb8aa3b, v133
	v_exp_f32_e32 v133, v133
	v_add_f32_e32 v132, v160, v132
	s_waitcnt lgkmcnt(0)
	v_mfma_f32_16x16x32_bf16 v[70:73], v[90:93], v[78:81], v[70:73]
	ds_read_b128 v[74:77], v231 offset:8832
	ds_read_b128 v[78:81], v231 offset:43648
	v_mul_f32_e32 v132, 0xbfb8aa3b, v132
	v_exp_f32_e32 v132, v132
	s_waitcnt lgkmcnt(1)
	v_mfma_f32_16x16x32_bf16 v[66:69], v[6:9], v[74:77], v[66:69]
	v_add_f32_e32 v133, 1.0, v133
	v_add_f32_e32 v132, 1.0, v132
	v_rcp_f32_e32 v132, v132
	s_waitcnt lgkmcnt(0)
	v_mfma_f32_16x16x32_bf16 v[70:73], v[6:9], v[78:81], v[70:73]
	ds_read_b128 v[74:77], v231 offset:8896
	ds_read_b128 v[78:81], v231 offset:43712
	s_waitcnt lgkmcnt(1)
	v_mfma_f32_16x16x32_bf16 v[114:117], v[2:5], v[74:77], v[66:69]
	s_waitcnt lgkmcnt(0)
	v_mfma_f32_16x16x32_bf16 v[110:113], v[2:5], v[78:81], v[70:73]
	s_nop 0
	ds_read_b128 v[66:69], v232
	s_nop 0
	ds_read_b128 v[70:73], v232 offset:34816
	ds_read_b128 v[74:77], v232 offset:64
	ds_read_b128 v[78:81], v232 offset:34880
	s_waitcnt lgkmcnt(3)
	v_mfma_f32_16x16x32_bf16 v[66:69], v[118:121], v[66:69], 0
	s_waitcnt lgkmcnt(2)
	v_mfma_f32_16x16x32_bf16 v[70:73], v[118:121], v[70:73], 0
	s_waitcnt lgkmcnt(1)
	v_mfma_f32_16x16x32_bf16 v[66:69], v[90:93], v[74:77], v[66:69]
	s_waitcnt lgkmcnt(0)
	v_mfma_f32_16x16x32_bf16 v[70:73], v[90:93], v[78:81], v[70:73]
	ds_read_b128 v[74:77], v232 offset:128
	ds_read_b128 v[78:81], v232 offset:34944
	s_waitcnt lgkmcnt(1)
	v_mfma_f32_16x16x32_bf16 v[66:69], v[6:9], v[74:77], v[66:69]
	s_waitcnt lgkmcnt(0)
	v_mfma_f32_16x16x32_bf16 v[70:73], v[6:9], v[78:81], v[70:73]
	ds_read_b128 v[74:77], v232 offset:192
	ds_read_b128 v[78:81], v232 offset:35008
	s_waitcnt lgkmcnt(1)
	v_mfma_f32_16x16x32_bf16 v[106:109], v[2:5], v[74:77], v[66:69]
	s_waitcnt lgkmcnt(0)
	v_mfma_f32_16x16x32_bf16 v[102:105], v[2:5], v[78:81], v[70:73]
	s_nop 0
	ds_read_b128 v[66:69], v231 offset:17408
	s_nop 0
	ds_read_b128 v[70:73], v231 offset:52224
	ds_read_b128 v[74:77], v231 offset:17472
	ds_read_b128 v[78:81], v231 offset:52288
	s_waitcnt lgkmcnt(3)
	v_mfma_f32_16x16x32_bf16 v[66:69], v[118:121], v[66:69], 0
	s_waitcnt lgkmcnt(2)
	v_mfma_f32_16x16x32_bf16 v[70:73], v[118:121], v[70:73], 0
	s_waitcnt lgkmcnt(1)
	v_mfma_f32_16x16x32_bf16 v[66:69], v[90:93], v[74:77], v[66:69]
	s_waitcnt lgkmcnt(0)
	v_mfma_f32_16x16x32_bf16 v[70:73], v[90:93], v[78:81], v[70:73]
	ds_read_b128 v[74:77], v231 offset:17536
	ds_read_b128 v[78:81], v231 offset:52352
	s_waitcnt lgkmcnt(1)
	v_mfma_f32_16x16x32_bf16 v[66:69], v[6:9], v[74:77], v[66:69]
	s_waitcnt lgkmcnt(0)
	v_mfma_f32_16x16x32_bf16 v[70:73], v[6:9], v[78:81], v[70:73]
	ds_read_b128 v[74:77], v231 offset:17600
	ds_read_b128 v[78:81], v231 offset:52416
	s_waitcnt lgkmcnt(1)
	v_mfma_f32_16x16x32_bf16 v[98:101], v[2:5], v[74:77], v[66:69]
	s_waitcnt lgkmcnt(0)
	v_mfma_f32_16x16x32_bf16 v[94:97], v[2:5], v[78:81], v[70:73]
	s_nop 0
	ds_read_b128 v[66:69], v231 offset:21760
	s_nop 0
	ds_read_b128 v[70:73], v231 offset:56576
	ds_read_b128 v[74:77], v231 offset:21824
	ds_read_b128 v[78:81], v231 offset:56640
	s_waitcnt lgkmcnt(3)
	v_mfma_f32_16x16x32_bf16 v[66:69], v[118:121], v[66:69], 0
	s_waitcnt lgkmcnt(2)
	v_mfma_f32_16x16x32_bf16 v[70:73], v[118:121], v[70:73], 0
	s_waitcnt lgkmcnt(1)
	v_mfma_f32_16x16x32_bf16 v[66:69], v[90:93], v[74:77], v[66:69]
	s_waitcnt lgkmcnt(0)
	v_mfma_f32_16x16x32_bf16 v[70:73], v[90:93], v[78:81], v[70:73]
	ds_read_b128 v[74:77], v231 offset:21888
	ds_read_b128 v[78:81], v231 offset:56704
	s_waitcnt lgkmcnt(1)
	v_mfma_f32_16x16x32_bf16 v[66:69], v[6:9], v[74:77], v[66:69]
	s_waitcnt lgkmcnt(0)
	v_mfma_f32_16x16x32_bf16 v[70:73], v[6:9], v[78:81], v[70:73]
	ds_read_b128 v[74:77], v231 offset:21952
	ds_read_b128 v[78:81], v231 offset:56768
	s_waitcnt lgkmcnt(1)
	v_mfma_f32_16x16x32_bf16 v[86:89], v[2:5], v[74:77], v[66:69]
	s_waitcnt lgkmcnt(0)
; #define LAS __attribute__((address_space(3)))
; __device__ __forceinline__ float fsig2(float x) { return __builtin_amdgcn_rcpf(1.0f + __builtin_amdgcn_exp2f(-LOG2E * x)); }
; template <int PASS> __device__ __forceinline__ void lru_wave_item(LAS unsigned char* lds, LAS unsigned char* vw, int b, int c, int h, const MixP& p, int lane, float (&Hrun)[8], bool cont) {
;     ...
;             for (int n = 0; n < 8; ++n) {
;                 aR[n] = (f32x4){0.f, 0.f, 0.f, 0.f}; aI[n] = (f32x4){0.f, 0.f, 0.f, 0.f};
; #pragma unroll
;                 for (int kk = 0; kk < 4; ++kk) {
;                     const bf16x8 ba = *(const LAS bf16x8*)(lds + WA_OFF + (16 * n + fr) * WROW + kk * 64 + fq * 16);
;                     const bf16x8 bx = *(const LAS bf16x8*)(lds + WX_OFF + (16 * n + fr) * WROW + kk * 64 + fq * 16);
;                     aR[n] = __builtin_amdgcn_mfma_f32_16x16x32_bf16(af[kk], ba, aR[n], 0, 0, 0);
;                     aI[n] = __builtin_amdgcn_mfma_f32_16x16x32_bf16(af[kk], bx, aI[n], 0, 0, 0);
;                 }
;             }
;         }
; #pragma unroll
;         for (int n = 0; n < 8; ++n) {
;             const f32x4 aVn = __builtin_amdgcn_mfma_f32_16x16x32_bf16(af[n >> 1], idf[n & 1], (f32x4){0.f, 0.f, 0.f, 0.f}, 0, 0, 0);
;             float av[4], bxv[4];
; #pragma unroll
;             for (int j = 0; j < 4; ++j) {
;                 const float r = fsig2(aR[n][j] + pba[n]), ig = fsig2(aI[n][j] + pbx[n]);
;                 const float a = __builtin_amdgcn_exp2f(r * pk8[n]), mult = __builtin_amdgcn_sqrtf(fmaxf(1.0f - a * a, 0.f));
;                 av[j] = a; bxv[j] = mult * ig * aVn[j];
;             }
;             const float H0 = bxv[0], H1 = av[1] * H0 + bxv[1], H2 = av[2] * H1 + bxv[2], H3 = av[3] * H2 + bxv[3];
;             const float A0 = av[0], A1 = av[1] * A0, A2 = av[2] * A1, A3 = av[3] * A2;
	v_mfma_f32_16x16x32_bf16 v[82:85], v[2:5], v[78:81], v[70:73]
	s_nop 0
	ds_read_b128 v[66:69], v231 offset:26112
	s_nop 0
	ds_read_b128 v[70:73], v231 offset:60928
	ds_read_b128 v[74:77], v231 offset:26176
	ds_read_b128 v[78:81], v231 offset:60992
	v_add_f32_e32 v86, v171, v86
	s_waitcnt lgkmcnt(3)
	v_mfma_f32_16x16x32_bf16 v[66:69], v[118:121], v[66:69], 0
	v_add_f32_e32 v87, v171, v87
	v_mul_f32_e32 v86, 0xbfb8aa3b, v86
	v_mul_f32_e32 v87, 0xbfb8aa3b, v87
	s_waitcnt lgkmcnt(2)
	v_mfma_f32_16x16x32_bf16 v[70:73], v[118:121], v[70:73], 0
	v_exp_f32_e32 v86, v86
	v_exp_f32_e32 v87, v87
	v_add_f32_e32 v82, v173, v82
	s_waitcnt lgkmcnt(1)
	v_mfma_f32_16x16x32_bf16 v[66:69], v[90:93], v[74:77], v[66:69]
	v_add_f32_e32 v86, 1.0, v86
	v_add_f32_e32 v87, 1.0, v87
	v_rcp_f32_e32 v86, v86
	s_waitcnt lgkmcnt(0)
	v_mfma_f32_16x16x32_bf16 v[70:73], v[90:93], v[78:81], v[70:73]
	ds_read_b128 v[74:77], v231 offset:26240
	ds_read_b128 v[78:81], v231 offset:61056
	v_rcp_f32_e32 v87, v87
	v_mul_f32_e32 v86, v175, v86
	s_waitcnt lgkmcnt(1)
	v_mfma_f32_16x16x32_bf16 v[66:69], v[6:9], v[74:77], v[66:69]
	ds_read_b128 v[74:77], v231 offset:26304
	ds_read_b128 v[138:141], v231 offset:61120
	v_add_f32_e32 v83, v173, v83
	v_mul_f32_e32 v87, v175, v87
	s_waitcnt lgkmcnt(2)
	v_mfma_f32_16x16x32_bf16 v[70:73], v[6:9], v[78:81], v[70:73]
	v_mul_f32_e32 v82, 0xbfb8aa3b, v82
	v_mul_f32_e32 v83, 0xbfb8aa3b, v83
	v_exp_f32_e32 v82, v82
	s_waitcnt lgkmcnt(1)
	v_mfma_f32_16x16x32_bf16 v[78:81], v[2:5], v[74:77], v[66:69]
	v_exp_f32_e32 v83, v83
	v_add_f32_e32 v85, v173, v85
	v_add_f32_e32 v82, 1.0, v82
	s_waitcnt lgkmcnt(0)
	v_mfma_f32_16x16x32_bf16 v[74:77], v[2:5], v[138:141], v[70:73]
	ds_read_b128 v[66:69], v233
	s_nop 1
	ds_read_b128 v[70:73], v233 offset:34816
	ds_read_b128 v[138:141], v233 offset:64
	ds_read_b128 v[184:187], v233 offset:34880
	v_add_f32_e32 v83, 1.0, v83
	s_waitcnt lgkmcnt(3)
	v_mfma_f32_16x16x32_bf16 v[66:69], v[118:121], v[66:69], 0
	v_rcp_f32_e32 v82, v82
	v_rcp_f32_e32 v83, v83
	v_mul_f32_e32 v85, 0xbfb8aa3b, v85
	s_waitcnt lgkmcnt(2)
	v_mfma_f32_16x16x32_bf16 v[70:73], v[118:121], v[70:73], 0
	v_exp_f32_e32 v85, v85
	s_nop 0
	v_add_f32_e32 v85, 1.0, v85
	s_waitcnt lgkmcnt(1)
	v_mfma_f32_16x16x32_bf16 v[66:69], v[90:93], v[138:141], v[66:69]
	s_waitcnt lgkmcnt(0)
	v_mfma_f32_16x16x32_bf16 v[70:73], v[90:93], v[184:187], v[70:73]
	ds_read_b128 v[138:141], v233 offset:128
	ds_read_b128 v[184:187], v233 offset:34944
	s_waitcnt lgkmcnt(1)
	v_mfma_f32_16x16x32_bf16 v[66:69], v[6:9], v[138:141], v[66:69]
	s_waitcnt lgkmcnt(0)
	v_mfma_f32_16x16x32_bf16 v[138:141], v[6:9], v[184:187], v[70:73]
	s_nop 2
	ds_read_b128 v[70:73], v233 offset:192
	ds_read_b128 v[184:187], v233 offset:35008
	s_waitcnt lgkmcnt(1)
	v_mfma_f32_16x16x32_bf16 v[70:73], v[2:5], v[70:73], v[66:69]
	s_waitcnt lgkmcnt(0)
	v_mfma_f32_16x16x32_bf16 v[66:69], v[2:5], v[184:187], v[138:141]
	v_exp_f32_e32 v186, v135
	s_nop 0
	v_fma_f32 v135, -v186, v186, 1.0
	v_max_f32_e32 v135, 0, v135
	v_sqrt_f32_e32 v135, v135
	v_mfma_f32_16x16x32_bf16 v[138:141], v[118:121], v[18:21], 0
	s_nop 1
	v_add_f32_e32 v66, v179, v66
	v_add_f32_e32 v67, v179, v67
	v_pk_mul_f32 v[130:131], v[130:131], v[134:135]
	v_add_f32_e32 v134, v158, v136
	v_mul_f32_e32 v134, 0xbfb8aa3b, v134
	v_exp_f32_e32 v134, v134
	v_pk_mul_f32 v[130:131], v[130:131], v[138:139]
	v_rcp_f32_e32 v136, v133
	v_mul_f32_e32 v66, 0xbfb8aa3b, v66
	v_add_f32_e32 v134, 1.0, v134
	v_rcp_f32_e32 v134, v134
	v_mul_f32_e32 v67, 0xbfb8aa3b, v67
	v_exp_f32_e32 v66, v66
	v_exp_f32_e32 v67, v67
	v_mul_f32_e32 v134, v162, v134
	v_exp_f32_e32 v139, v134
	v_add_f32_e32 v134, v158, v137
	v_mul_f32_e32 v134, 0xbfb8aa3b, v134
	v_exp_f32_e32 v134, v134
	v_add_f32_e32 v66, 1.0, v66
	v_add_f32_e32 v67, 1.0, v67
	v_rcp_f32_e32 v66, v66
	v_add_f32_e32 v134, 1.0, v134
	v_rcp_f32_e32 v134, v134
	v_rcp_f32_e32 v67, v67
	v_add_f32_e32 v69, v179, v69
	v_mul_f32_e32 v69, 0xbfb8aa3b, v69
	v_mul_f32_e32 v133, v162, v134
	v_exp_f32_e32 v185, v133
	v_fma_f32 v133, v186, v130, v131
	v_fma_f32 v131, -v139, v139, 1.0
	v_max_f32_e32 v131, 0, v131
	v_sqrt_f32_e32 v138, v131
	v_fma_f32 v131, -v185, v185, 1.0
	v_max_f32_e32 v131, 0, v131
	v_sqrt_f32_e32 v184, v131
	v_pk_mul_f32 v[134:135], v[132:133], v[138:139]
	v_mul_f32_e32 v131, v186, v236
	v_fmac_f32_e32 v135, v134, v140
	v_mov_b32_e32 v137, v135
	v_pk_mul_f32 v[136:137], v[136:137], v[184:185]
	v_mul_f32_e32 v132, v139, v131
	v_fmac_f32_e32 v137, v136, v141
	v_mfma_f32_16x16x32_bf16 v[138:141], v[118:121], v[22:25], 0
	v_add_f32_e32 v118, v159, v126
	v_mul_f32_e32 v118, 0xbfb8aa3b, v118
	v_exp_f32_e32 v118, v118
	v_mul_f32_e32 v134, v185, v132
	ds_bpermute_b32 v188, v0, v134
	ds_bpermute_b32 v192, v0, v137
	v_add_f32_e32 v118, 1.0, v118
	v_rcp_f32_e32 v119, v118
	v_add_f32_e32 v118, v161, v122
	v_mul_f32_e32 v118, 0xbfb8aa3b, v118
	v_exp_f32_e32 v118, v118
	v_mul_f32_e32 v119, v163, v119
	v_exp_f32_e32 v136, v119
	v_add_f32_e32 v122, v161, v125
	v_add_f32_e32 v118, 1.0, v118
	v_rcp_f32_e32 v118, v118
	v_fma_f32 v119, -v136, v136, 1.0
	v_max_f32_e32 v119, 0, v119
	v_sqrt_f32_e32 v120, v119
	v_add_f32_e32 v119, v159, v127
	v_mul_f32_e32 v119, 0xbfb8aa3b, v119
	v_exp_f32_e32 v119, v119
	v_mul_f32_e32 v122, 0xbfb8aa3b, v122
	v_exp_f32_e32 v122, v122
	ds_bpermute_b32 v190, v0, v134 offset:64
	v_add_f32_e32 v119, 1.0, v119
	v_rcp_f32_e32 v121, v119
	v_add_f32_e32 v119, v161, v123
	v_mul_f32_e32 v119, 0xbfb8aa3b, v119
	v_exp_f32_e32 v119, v119
	v_mul_f32_e32 v121, v163, v121
	v_exp_f32_e32 v185, v121
	v_add_f32_e32 v122, 1.0, v122
	v_add_f32_e32 v119, 1.0, v119
	v_rcp_f32_e32 v119, v119
	v_fma_f32 v121, -v185, v185, 1.0
; __device__ __forceinline__ float fsig2(float x) { return __builtin_amdgcn_rcpf(1.0f + __builtin_amdgcn_exp2f(-LOG2E * x)); }
; template <int PASS> __device__ __forceinline__ void lru_wave_item(LAS unsigned char* lds, LAS unsigned char* vw, int b, int c, int h, const MixP& p, int lane, float (&Hrun)[8], bool cont) {
;     ...
;         for (int n = 0; n < 8; ++n) {
;             const f32x4 aVn = __builtin_amdgcn_mfma_f32_16x16x32_bf16(af[n >> 1], idf[n & 1], (f32x4){0.f, 0.f, 0.f, 0.f}, 0, 0, 0);
;             float av[4], bxv[4];
; #pragma unroll
;             for (int j = 0; j < 4; ++j) {
;                 const float r = fsig2(aR[n][j] + pba[n]), ig = fsig2(aI[n][j] + pbx[n]);
;                 const float a = __builtin_amdgcn_exp2f(r * pk8[n]), mult = __builtin_amdgcn_sqrtf(fmaxf(1.0f - a * a, 0.f));
;                 av[j] = a; bxv[j] = mult * ig * aVn[j];
;             }
;             const float H0 = bxv[0], H1 = av[1] * H0 + bxv[1], H2 = av[2] * H1 + bxv[2], H3 = av[3] * H2 + bxv[3];
;             const float A0 = av[0], A1 = av[1] * A0, A2 = av[2] * A1, A3 = av[3] * A2;
;             float At[4], Ht[4];
; #pragma unroll
;             for (int q = 0; q < 4; ++q) { At[q] = __shfl(A3, fr + 16 * q); Ht[q] = __shfl(H3, fr + 16 * q); }
;             const float c0 = Hrun[n], c1 = At[0] * c0 + Ht[0], c2 = At[1] * c1 + Ht[1], c3 = At[2] * c2 + Ht[2], c4 = At[3] * c3 + Ht[3];
;             Hrun[n] = c4;
;             if (PASS == 1) Arun[n] *= (At[0] * At[1]) * (At[2] * At[3]);
;             if (PASS == 2) {
;                 const float cin = fq == 0 ? c0 : (fq == 1 ? c1 : (fq == 2 ? c2 : c3));
;                 aR[n][0] = H0 + A0 * cin; aR[n][1] = H1 + A1 * cin; aR[n][2] = H2 + A2 * cin; aR[n][3] = H3 + A3 * cin;
;             }
	v_max_f32_e32 v121, 0, v121
	v_sqrt_f32_e32 v121, v121
	ds_bpermute_b32 v196, v0, v137 offset:64
	ds_bpermute_b32 v194, v0, v134 offset:128
	ds_bpermute_b32 v198, v0, v137 offset:128
	v_pk_mul_f32 v[118:119], v[118:119], v[120:121]
	v_add_f32_e32 v120, v159, v128
	v_mul_f32_e32 v120, 0xbfb8aa3b, v120
	v_exp_f32_e32 v120, v120
	v_pk_mul_f32 v[118:119], v[118:119], v[138:139]
	ds_bpermute_b32 v186, v0, v137 offset:192
	v_exp_f32_e32 v69, v69
	v_add_f32_e32 v120, 1.0, v120
	v_rcp_f32_e32 v121, v120
	v_add_f32_e32 v120, v161, v124
	v_mul_f32_e32 v120, 0xbfb8aa3b, v120
	v_exp_f32_e32 v120, v120
	v_mul_f32_e32 v121, v163, v121
	v_exp_f32_e32 v127, v121
	v_add_f32_e32 v121, v159, v129
	v_mul_f32_e32 v121, 0xbfb8aa3b, v121
	v_exp_f32_e32 v121, v121
	v_add_f32_e32 v120, 1.0, v120
	v_rcp_f32_e32 v120, v120
	v_rcp_f32_e32 v124, v122
	v_add_f32_e32 v121, 1.0, v121
	v_rcp_f32_e32 v121, v121
	v_add_f32_e32 v69, 1.0, v69
	ds_bpermute_b32 v184, v0, v134 offset:192
	v_mul_f32_e32 v121, v163, v121
	v_exp_f32_e32 v129, v121
	v_fma_f32 v121, v185, v118, v119
	v_fma_f32 v119, -v127, v127, 1.0
	v_max_f32_e32 v119, 0, v119
	v_sqrt_f32_e32 v126, v119
	v_fma_f32 v119, -v129, v129, 1.0
	v_max_f32_e32 v119, 0, v119
	v_sqrt_f32_e32 v128, v119
	v_pk_mul_f32 v[122:123], v[120:121], v[126:127]
	v_mul_f32_e32 v119, v185, v136
	v_fmac_f32_e32 v123, v122, v140
	v_mov_b32_e32 v125, v123
	v_pk_mul_f32 v[124:125], v[124:125], v[128:129]
	v_mul_f32_e32 v120, v127, v119
	v_fmac_f32_e32 v125, v124, v141
	v_mul_f32_e32 v122, v129, v120
	ds_bpermute_b32 v189, v0, v122
	ds_bpermute_b32 v193, v0, v125
	ds_bpermute_b32 v191, v0, v122 offset:64
	ds_bpermute_b32 v197, v0, v125 offset:64
	ds_bpermute_b32 v195, v0, v122 offset:128
	ds_bpermute_b32 v199, v0, v125 offset:128
	s_waitcnt lgkmcnt(4)
	v_pk_fma_f32 v[128:129], v[10:11], v[188:189], v[192:193]
	ds_bpermute_b32 v187, v0, v125 offset:192
	s_waitcnt lgkmcnt(3)
	v_pk_fma_f32 v[138:139], v[128:129], v[190:191], v[196:197]
	ds_bpermute_b32 v185, v0, v122 offset:192
	s_waitcnt lgkmcnt(2)
	v_pk_fma_f32 v[126:127], v[138:139], v[194:195], v[198:199]
	s_nop 0
	v_cndmask_b32_e64 v124, v126, v138, s[8:9]
	v_cndmask_b32_e64 v124, v124, v128, s[6:7]
	v_cndmask_b32_e64 v10, v124, v10, s[4:5]
	v_fmac_f32_e32 v130, v236, v10
	v_fmac_f32_e32 v133, v131, v10
	v_fmac_f32_e32 v135, v132, v10
	v_fmac_f32_e32 v137, v134, v10
	v_cndmask_b32_e64 v10, v127, v139, s[8:9]
	v_cndmask_b32_e64 v10, v10, v129, s[6:7]
	v_cndmask_b32_e64 v10, v10, v11, s[4:5]
	v_fmac_f32_e32 v118, v136, v10
	v_fmac_f32_e32 v121, v119, v10
	v_fmac_f32_e32 v123, v120, v10
	v_fmac_f32_e32 v125, v122, v10
	v_add_f32_e32 v10, v164, v114
	v_mul_f32_e32 v10, 0xbfb8aa3b, v10
	v_exp_f32_e32 v10, v10
	v_mfma_f32_16x16x32_bf16 v[138:141], v[90:93], v[18:21], 0
	v_add_f32_e32 v10, 1.0, v10
	v_rcp_f32_e32 v11, v10
	v_add_f32_e32 v10, v166, v110
	v_mul_f32_e32 v10, 0xbfb8aa3b, v10
	v_exp_f32_e32 v10, v10
	v_mul_f32_e32 v11, v168, v11
	v_exp_f32_e32 v119, v11
	v_add_f32_e32 v10, 1.0, v10
	v_rcp_f32_e32 v10, v10
	v_fma_f32 v11, -v119, v119, 1.0
	v_max_f32_e32 v11, 0, v11
	v_sqrt_f32_e32 v110, v11
	v_add_f32_e32 v11, v164, v115
	v_mul_f32_e32 v11, 0xbfb8aa3b, v11
	v_exp_f32_e32 v11, v11
	s_nop 0
	v_add_f32_e32 v11, 1.0, v11
	v_rcp_f32_e32 v114, v11
	v_add_f32_e32 v11, v166, v111
	v_mul_f32_e32 v11, 0xbfb8aa3b, v11
	v_exp_f32_e32 v11, v11
	v_mul_f32_e32 v111, v168, v114
	v_exp_f32_e32 v120, v111
	v_add_f32_e32 v11, 1.0, v11
	v_rcp_f32_e32 v11, v11
	v_fma_f32 v111, -v120, v120, 1.0
	v_max_f32_e32 v111, 0, v111
	v_sqrt_f32_e32 v111, v111
	s_nop 0
	v_pk_mul_f32 v[10:11], v[10:11], v[110:111]
	v_add_f32_e32 v110, v164, v116
	v_mul_f32_e32 v110, 0xbfb8aa3b, v110
	v_exp_f32_e32 v110, v110
	v_pk_mul_f32 v[10:11], v[10:11], v[138:139]
	v_add_f32_e32 v110, 1.0, v110
	v_rcp_f32_e32 v111, v110
	v_add_f32_e32 v110, v166, v112
	v_mul_f32_e32 v110, 0xbfb8aa3b, v110
	v_exp_f32_e32 v110, v110
	v_mul_f32_e32 v111, v168, v111
	v_exp_f32_e32 v129, v111
	v_add_f32_e32 v111, v164, v117
	v_mul_f32_e32 v111, 0xbfb8aa3b, v111
	v_exp_f32_e32 v111, v111
	v_add_f32_e32 v112, v166, v113
	v_mul_f32_e32 v112, 0xbfb8aa3b, v112
	v_exp_f32_e32 v112, v112
	v_add_f32_e32 v111, 1.0, v111
	v_rcp_f32_e32 v111, v111
	v_add_f32_e32 v110, 1.0, v110
	v_rcp_f32_e32 v110, v110
	v_add_f32_e32 v112, 1.0, v112
	v_mul_f32_e32 v111, v168, v111
	v_exp_f32_e32 v117, v111
	v_fma_f32 v111, v120, v10, v11
	v_fma_f32 v11, -v129, v129, 1.0
	v_max_f32_e32 v11, 0, v11
	v_sqrt_f32_e32 v128, v11
	v_fma_f32 v11, -v117, v117, 1.0
	v_max_f32_e32 v11, 0, v11
	v_rcp_f32_e32 v114, v112
	v_sqrt_f32_e32 v116, v11
	v_pk_mul_f32 v[112:113], v[110:111], v[128:129]
	v_mul_f32_e32 v11, v120, v119
	v_fmac_f32_e32 v113, v112, v140
	v_mov_b32_e32 v115, v113
	v_pk_mul_f32 v[114:115], v[114:115], v[116:117]
	v_mul_f32_e32 v110, v129, v11
	v_fmac_f32_e32 v115, v114, v141
	v_mfma_f32_16x16x32_bf16 v[138:141], v[90:93], v[22:25], 0
	v_add_f32_e32 v90, v165, v106
	v_mul_f32_e32 v90, 0xbfb8aa3b, v90
	v_exp_f32_e32 v90, v90
	v_mul_f32_e32 v112, v117, v110
	ds_bpermute_b32 v188, v0, v112
	ds_bpermute_b32 v190, v0, v115
	v_add_f32_e32 v90, 1.0, v90
	v_rcp_f32_e32 v91, v90
	v_add_f32_e32 v90, v167, v102
	v_mul_f32_e32 v90, 0xbfb8aa3b, v90
	v_exp_f32_e32 v90, v90
	v_mul_f32_e32 v91, v169, v91
	v_exp_f32_e32 v114, v91
	v_add_f32_e32 v102, v167, v105
	v_add_f32_e32 v90, 1.0, v90
	v_rcp_f32_e32 v90, v90
	v_fma_f32 v91, -v114, v114, 1.0
	v_max_f32_e32 v91, 0, v91
	v_sqrt_f32_e32 v92, v91
	v_add_f32_e32 v91, v165, v107
	v_mul_f32_e32 v91, 0xbfb8aa3b, v91
	v_exp_f32_e32 v91, v91
	v_mul_f32_e32 v102, 0xbfb8aa3b, v102
	v_exp_f32_e32 v102, v102
	ds_bpermute_b32 v192, v0, v112 offset:64
; __device__ __forceinline__ float fsig2(float x) { return __builtin_amdgcn_rcpf(1.0f + __builtin_amdgcn_exp2f(-LOG2E * x)); }
; template <int PASS> __device__ __forceinline__ void lru_wave_item(LAS unsigned char* lds, LAS unsigned char* vw, int b, int c, int h, const MixP& p, int lane, float (&Hrun)[8], bool cont) {
;     ...
;         for (int n = 0; n < 8; ++n) {
;             const f32x4 aVn = __builtin_amdgcn_mfma_f32_16x16x32_bf16(af[n >> 1], idf[n & 1], (f32x4){0.f, 0.f, 0.f, 0.f}, 0, 0, 0);
;             float av[4], bxv[4];
; #pragma unroll
;             for (int j = 0; j < 4; ++j) {
;                 const float r = fsig2(aR[n][j] + pba[n]), ig = fsig2(aI[n][j] + pbx[n]);
;                 const float a = __builtin_amdgcn_exp2f(r * pk8[n]), mult = __builtin_amdgcn_sqrtf(fmaxf(1.0f - a * a, 0.f));
;                 av[j] = a; bxv[j] = mult * ig * aVn[j];
;             }
;             const float H0 = bxv[0], H1 = av[1] * H0 + bxv[1], H2 = av[2] * H1 + bxv[2], H3 = av[3] * H2 + bxv[3];
;             const float A0 = av[0], A1 = av[1] * A0, A2 = av[2] * A1, A3 = av[3] * A2;
;             float At[4], Ht[4];
; #pragma unroll
;             for (int q = 0; q < 4; ++q) { At[q] = __shfl(A3, fr + 16 * q); Ht[q] = __shfl(H3, fr + 16 * q); }
;             const float c0 = Hrun[n], c1 = At[0] * c0 + Ht[0], c2 = At[1] * c1 + Ht[1], c3 = At[2] * c2 + Ht[2], c4 = At[3] * c3 + Ht[3];
;             Hrun[n] = c4;
;             if (PASS == 1) Arun[n] *= (At[0] * At[1]) * (At[2] * At[3]);
;             if (PASS == 2) {
;                 const float cin = fq == 0 ? c0 : (fq == 1 ? c1 : (fq == 2 ? c2 : c3));
;                 aR[n][0] = H0 + A0 * cin; aR[n][1] = H1 + A1 * cin; aR[n][2] = H2 + A2 * cin; aR[n][3] = H3 + A3 * cin;
;             }
	v_add_f32_e32 v91, 1.0, v91
	v_rcp_f32_e32 v93, v91
	v_add_f32_e32 v91, v167, v103
	v_mul_f32_e32 v91, 0xbfb8aa3b, v91
	v_exp_f32_e32 v91, v91
	v_mul_f32_e32 v93, v169, v93
	v_exp_f32_e32 v117, v93
	v_add_f32_e32 v102, 1.0, v102
	v_add_f32_e32 v91, 1.0, v91
	v_rcp_f32_e32 v91, v91
	v_fma_f32 v93, -v117, v117, 1.0
	v_max_f32_e32 v93, 0, v93
	v_sqrt_f32_e32 v93, v93
	ds_bpermute_b32 v194, v0, v115 offset:64
	ds_bpermute_b32 v196, v0, v112 offset:128
	ds_bpermute_b32 v198, v0, v115 offset:128
	v_pk_mul_f32 v[90:91], v[90:91], v[92:93]
	v_add_f32_e32 v92, v165, v108
	v_mul_f32_e32 v92, 0xbfb8aa3b, v92
	v_exp_f32_e32 v92, v92
	v_pk_mul_f32 v[90:91], v[90:91], v[138:139]
	ds_bpermute_b32 v128, v0, v115 offset:192
	ds_bpermute_b32 v116, v0, v112 offset:192
	v_add_f32_e32 v92, 1.0, v92
	v_rcp_f32_e32 v93, v92
	v_add_f32_e32 v92, v167, v104
	v_mul_f32_e32 v92, 0xbfb8aa3b, v92
	v_exp_f32_e32 v92, v92
	v_mul_f32_e32 v93, v169, v93
	v_exp_f32_e32 v107, v93
	v_add_f32_e32 v93, v165, v109
	v_mul_f32_e32 v93, 0xbfb8aa3b, v93
	v_exp_f32_e32 v93, v93
	v_add_f32_e32 v92, 1.0, v92
	v_rcp_f32_e32 v92, v92
	v_rcp_f32_e32 v104, v102
	v_add_f32_e32 v93, 1.0, v93
	v_rcp_f32_e32 v93, v93
	s_nop 0
	v_mul_f32_e32 v93, v169, v93
	v_exp_f32_e32 v109, v93
	v_fma_f32 v93, v117, v90, v91
	v_fma_f32 v91, -v107, v107, 1.0
	v_max_f32_e32 v91, 0, v91
	v_sqrt_f32_e32 v106, v91
	v_fma_f32 v91, -v109, v109, 1.0
	v_max_f32_e32 v91, 0, v91
	v_sqrt_f32_e32 v108, v91
	v_pk_mul_f32 v[102:103], v[92:93], v[106:107]
	v_mul_f32_e32 v91, v117, v114
	v_fmac_f32_e32 v103, v102, v140
	v_mov_b32_e32 v105, v103
	v_pk_mul_f32 v[104:105], v[104:105], v[108:109]
	v_mul_f32_e32 v92, v107, v91
	v_fmac_f32_e32 v105, v104, v141
	v_mul_f32_e32 v102, v109, v92
	ds_bpermute_b32 v189, v0, v102
	ds_bpermute_b32 v191, v0, v105
	ds_bpermute_b32 v193, v0, v102 offset:64
	ds_bpermute_b32 v195, v0, v105 offset:64
	ds_bpermute_b32 v197, v0, v102 offset:128
	ds_bpermute_b32 v199, v0, v105 offset:128
	s_waitcnt lgkmcnt(4)
	v_pk_fma_f32 v[108:109], v[12:13], v[188:189], v[190:191]
	ds_bpermute_b32 v129, v0, v105 offset:192
	s_waitcnt lgkmcnt(3)
	v_pk_fma_f32 v[138:139], v[108:109], v[192:193], v[194:195]
	ds_bpermute_b32 v117, v0, v102 offset:192
	s_waitcnt lgkmcnt(2)
	v_pk_fma_f32 v[106:107], v[138:139], v[196:197], v[198:199]
	s_nop 0
	v_cndmask_b32_e64 v104, v106, v138, s[8:9]
	v_cndmask_b32_e64 v104, v104, v108, s[6:7]
	v_cndmask_b32_e64 v12, v104, v12, s[4:5]
	v_fmac_f32_e32 v111, v11, v12
	v_cndmask_b32_e64 v11, v107, v139, s[8:9]
	v_cndmask_b32_e64 v11, v11, v109, s[6:7]
	v_cndmask_b32_e64 v11, v11, v13, s[4:5]
	v_fmac_f32_e32 v90, v114, v11
	v_fmac_f32_e32 v93, v91, v11
	v_fmac_f32_e32 v103, v92, v11
	v_fmac_f32_e32 v105, v102, v11
	v_add_f32_e32 v11, v170, v98
	v_mul_f32_e32 v11, 0xbfb8aa3b, v11
	v_exp_f32_e32 v11, v11
	v_fmac_f32_e32 v10, v119, v12
	v_fmac_f32_e32 v113, v110, v12
	v_fmac_f32_e32 v115, v112, v12
	v_add_f32_e32 v11, 1.0, v11
	v_rcp_f32_e32 v11, v11
	v_add_f32_e32 v12, v172, v94
	v_mul_f32_e32 v12, 0xbfb8aa3b, v12
	v_exp_f32_e32 v12, v12
	v_mul_f32_e32 v11, v174, v11
	v_exp_f32_e32 v11, v11
	v_mfma_f32_16x16x32_bf16 v[138:141], v[6:9], v[18:21], 0
	v_add_f32_e32 v12, 1.0, v12
	v_rcp_f32_e32 v12, v12
	v_fma_f32 v13, -v11, v11, 1.0
	v_max_f32_e32 v13, 0, v13
	v_sqrt_f32_e32 v94, v13
	v_add_f32_e32 v13, v170, v99
	v_mul_f32_e32 v13, 0xbfb8aa3b, v13
	v_exp_f32_e32 v13, v13
	v_mfma_f32_16x16x32_bf16 v[6:9], v[6:9], v[22:25], 0
	v_add_f32_e32 v13, 1.0, v13
	v_rcp_f32_e32 v91, v13
	v_add_f32_e32 v13, v172, v95
	v_mul_f32_e32 v13, 0xbfb8aa3b, v13
	v_exp_f32_e32 v13, v13
	v_mul_f32_e32 v91, v174, v91
	v_exp_f32_e32 v91, v91
	v_add_f32_e32 v13, 1.0, v13
	v_rcp_f32_e32 v13, v13
	v_fma_f32 v92, -v91, v91, 1.0
	v_max_f32_e32 v92, 0, v92
	v_sqrt_f32_e32 v95, v92
	v_add_f32_e32 v92, v170, v100
	v_mul_f32_e32 v92, 0xbfb8aa3b, v92
	v_exp_f32_e32 v92, v92
	v_pk_mul_f32 v[12:13], v[12:13], v[94:95]
	v_add_f32_e32 v95, v172, v97
	v_mul_f32_e32 v95, 0xbfb8aa3b, v95
	v_add_f32_e32 v92, 1.0, v92
	v_rcp_f32_e32 v92, v92
	v_add_f32_e32 v94, v172, v96
	v_exp_f32_e32 v95, v95
	v_mul_f32_e32 v94, 0xbfb8aa3b, v94
	v_mul_f32_e32 v92, v174, v92
	v_exp_f32_e32 v109, v92
	v_exp_f32_e32 v94, v94
	v_pk_mul_f32 v[12:13], v[12:13], v[138:139]
	v_add_f32_e32 v95, 1.0, v95
	v_rcp_f32_e32 v98, v95
	v_fma_f32 v95, v91, v12, v13
	v_fma_f32 v13, -v109, v109, 1.0
	v_add_f32_e32 v94, 1.0, v94
	v_max_f32_e32 v13, 0, v13
	v_rcp_f32_e32 v94, v94
	v_sqrt_f32_e32 v108, v13
	v_add_f32_e32 v92, v170, v101
	v_mul_f32_e32 v92, 0xbfb8aa3b, v92
	v_exp_f32_e32 v92, v92
	v_pk_mul_f32 v[96:97], v[94:95], v[108:109]
	v_exp_f32_e32 v94, v86
	v_fmac_f32_e32 v97, v96, v140
	v_exp_f32_e32 v96, v87
	v_add_f32_e32 v92, 1.0, v92
	v_fma_f32 v86, -v94, v94, 1.0
	v_max_f32_e32 v86, 0, v86
	v_fma_f32 v87, -v96, v96, 1.0
	v_max_f32_e32 v87, 0, v87
	v_sqrt_f32_e32 v86, v86
	v_sqrt_f32_e32 v87, v87
	v_rcp_f32_e32 v92, v92
	v_mov_b32_e32 v99, v97
	v_pk_mul_f32 v[82:83], v[82:83], v[86:87]
	s_nop 0
	v_pk_mul_f32 v[82:83], v[82:83], v[6:7]
	v_add_f32_e32 v6, v171, v88
	v_mul_f32_e32 v6, 0xbfb8aa3b, v6
	v_exp_f32_e32 v6, v6
	v_add_f32_e32 v7, v173, v84
	v_mul_f32_e32 v7, 0xbfb8aa3b, v7
	v_exp_f32_e32 v7, v7
	v_add_f32_e32 v6, 1.0, v6
	v_rcp_f32_e32 v6, v6
	v_mul_f32_e32 v92, v174, v92
	v_add_f32_e32 v7, 1.0, v7
	v_rcp_f32_e32 v84, v7
	v_mul_f32_e32 v6, v175, v6
	v_exp_f32_e32 v7, v6
	v_add_f32_e32 v6, v171, v89
	v_mul_f32_e32 v6, 0xbfb8aa3b, v6
	v_exp_f32_e32 v6, v6
	v_exp_f32_e32 v101, v92
	v_rcp_f32_e32 v88, v85
	v_fma_f32 v85, v96, v82, v83
	v_add_f32_e32 v6, 1.0, v6
	v_rcp_f32_e32 v6, v6
	v_fma_f32 v13, -v101, v101, 1.0
	v_max_f32_e32 v13, 0, v13
	v_sqrt_f32_e32 v100, v13
	v_mul_f32_e32 v6, v175, v6
	v_exp_f32_e32 v197, v6
	v_fma_f32 v6, -v7, v7, 1.0
	v_max_f32_e32 v6, 0, v6
	v_sqrt_f32_e32 v6, v6
	v_mul_f32_e32 v13, v91, v11
	v_mul_f32_e32 v83, v96, v94
	v_pk_mul_f32 v[98:99], v[98:99], v[100:101]
	v_pk_mul_f32 v[86:87], v[84:85], v[6:7]
	v_fma_f32 v6, -v197, v197, 1.0
	v_max_f32_e32 v6, 0, v6
	v_sqrt_f32_e32 v196, v6
	v_fmac_f32_e32 v87, v86, v8
	v_mov_b32_e32 v89, v87
	v_mul_f32_e32 v91, v109, v13
	v_pk_mul_f32 v[88:89], v[88:89], v[196:197]
	v_mul_f32_e32 v84, v7, v83
	v_fmac_f32_e32 v99, v98, v141
	v_mul_f32_e32 v92, v101, v91
	v_fmac_f32_e32 v89, v88, v9
	v_mul_f32_e32 v86, v197, v84
	ds_bpermute_b32 v138, v0, v92
	ds_bpermute_b32 v140, v0, v99
	ds_bpermute_b32 v139, v0, v86
	ds_bpermute_b32 v141, v0, v89
	ds_bpermute_b32 v188, v0, v92 offset:64
	ds_bpermute_b32 v190, v0, v99 offset:64
	ds_bpermute_b32 v189, v0, v86 offset:64
	ds_bpermute_b32 v191, v0, v89 offset:64
	ds_bpermute_b32 v192, v0, v92 offset:128
	ds_bpermute_b32 v194, v0, v99 offset:128
	ds_bpermute_b32 v193, v0, v86 offset:128
	ds_bpermute_b32 v195, v0, v89 offset:128
	s_waitcnt lgkmcnt(8)
; __device__ __forceinline__ float fsig2(float x) { return __builtin_amdgcn_rcpf(1.0f + __builtin_amdgcn_exp2f(-LOG2E * x)); }
; template <int PASS> __device__ __forceinline__ void lru_wave_item(LAS unsigned char* lds, LAS unsigned char* vw, int b, int c, int h, const MixP& p, int lane, float (&Hrun)[8], bool cont) {
;     ...
;         for (int n = 0; n < 8; ++n) {
;             const f32x4 aVn = __builtin_amdgcn_mfma_f32_16x16x32_bf16(af[n >> 1], idf[n & 1], (f32x4){0.f, 0.f, 0.f, 0.f}, 0, 0, 0);
;             float av[4], bxv[4];
; #pragma unroll
;             for (int j = 0; j < 4; ++j) {
;                 const float r = fsig2(aR[n][j] + pba[n]), ig = fsig2(aI[n][j] + pbx[n]);
;                 const float a = __builtin_amdgcn_exp2f(r * pk8[n]), mult = __builtin_amdgcn_sqrtf(fmaxf(1.0f - a * a, 0.f));
;                 av[j] = a; bxv[j] = mult * ig * aVn[j];
;             }
;             const float H0 = bxv[0], H1 = av[1] * H0 + bxv[1], H2 = av[2] * H1 + bxv[2], H3 = av[3] * H2 + bxv[3];
;             const float A0 = av[0], A1 = av[1] * A0, A2 = av[2] * A1, A3 = av[3] * A2;
;             float At[4], Ht[4];
; #pragma unroll
;             for (int q = 0; q < 4; ++q) { At[q] = __shfl(A3, fr + 16 * q); Ht[q] = __shfl(H3, fr + 16 * q); }
;             const float c0 = Hrun[n], c1 = At[0] * c0 + Ht[0], c2 = At[1] * c1 + Ht[1], c3 = At[2] * c2 + Ht[2], c4 = At[3] * c3 + Ht[3];
;             Hrun[n] = c4;
;             if (PASS == 1) Arun[n] *= (At[0] * At[1]) * (At[2] * At[3]);
;             if (PASS == 2) {
;                 const float cin = fq == 0 ? c0 : (fq == 1 ? c1 : (fq == 2 ? c2 : c3));
;                 aR[n][0] = H0 + A0 * cin; aR[n][1] = H1 + A1 * cin; aR[n][2] = H2 + A2 * cin; aR[n][3] = H3 + A3 * cin;
;             }
	v_pk_fma_f32 v[8:9], v[14:15], v[138:139], v[140:141]
	ds_bpermute_b32 v108, v0, v99 offset:192
	s_waitcnt lgkmcnt(5)
	v_pk_fma_f32 v[138:139], v[8:9], v[188:189], v[190:191]
	ds_bpermute_b32 v109, v0, v89 offset:192
	s_waitcnt lgkmcnt(2)
	v_pk_fma_f32 v[6:7], v[138:139], v[192:193], v[194:195]
	ds_bpermute_b32 v100, v0, v92 offset:192
	v_cndmask_b32_e64 v88, v6, v138, s[8:9]
	v_cndmask_b32_e64 v8, v88, v8, s[6:7]
	v_cndmask_b32_e64 v8, v8, v14, s[4:5]
	v_fmac_f32_e32 v12, v11, v8
	v_fmac_f32_e32 v95, v13, v8
	v_fmac_f32_e32 v97, v91, v8
	v_fmac_f32_e32 v99, v92, v8
	v_cndmask_b32_e64 v8, v7, v139, s[8:9]
	v_cndmask_b32_e64 v8, v8, v9, s[6:7]
	v_cndmask_b32_e64 v8, v8, v15, s[4:5]
	v_fmac_f32_e32 v82, v94, v8
	v_fmac_f32_e32 v85, v83, v8
	v_fmac_f32_e32 v87, v84, v8
	v_fmac_f32_e32 v89, v86, v8
	v_add_f32_e32 v8, v176, v78
	v_mul_f32_e32 v8, 0xbfb8aa3b, v8
	v_exp_f32_e32 v8, v8
	v_mfma_f32_16x16x32_bf16 v[138:141], v[2:5], v[18:21], 0
	ds_bpermute_b32 v101, v0, v86 offset:192
	v_add_f32_e32 v8, 1.0, v8
	v_rcp_f32_e32 v9, v8
	v_add_f32_e32 v8, v178, v74
	v_mul_f32_e32 v8, 0xbfb8aa3b, v8
	v_exp_f32_e32 v8, v8
	v_mul_f32_e32 v9, v180, v9
	v_exp_f32_e32 v11, v9
	v_mfma_f32_16x16x32_bf16 v[2:5], v[2:5], v[22:25], 0
	v_add_f32_e32 v8, 1.0, v8
	v_rcp_f32_e32 v8, v8
	v_fma_f32 v9, -v11, v11, 1.0
	v_max_f32_e32 v9, 0, v9
	v_sqrt_f32_e32 v14, v9
	v_add_f32_e32 v9, v176, v79
	v_mul_f32_e32 v9, 0xbfb8aa3b, v9
	v_exp_f32_e32 v9, v9
	s_waitcnt lgkmcnt(0)
	v_pk_fma_f32 v[6:7], v[6:7], v[100:101], v[108:109]
	v_add_f32_e32 v9, 1.0, v9
	v_rcp_f32_e32 v13, v9
	v_add_f32_e32 v9, v178, v75
	v_mul_f32_e32 v9, 0xbfb8aa3b, v9
	v_exp_f32_e32 v9, v9
	v_mul_f32_e32 v13, v180, v13
	v_exp_f32_e32 v13, v13
	v_add_f32_e32 v75, v178, v77
	v_add_f32_e32 v9, 1.0, v9
	v_rcp_f32_e32 v9, v9
	v_fma_f32 v15, -v13, v13, 1.0
	v_max_f32_e32 v15, 0, v15
	v_sqrt_f32_e32 v15, v15
	v_mul_f32_e32 v75, 0xbfb8aa3b, v75
	v_exp_f32_e32 v75, v75
	v_pk_mul_f32 v[8:9], v[8:9], v[14:15]
	s_nop 0
	v_pk_mul_f32 v[14:15], v[8:9], v[138:139]
	v_add_f32_e32 v8, v176, v80
	v_mul_f32_e32 v8, 0xbfb8aa3b, v8
	v_exp_f32_e32 v8, v8
	v_add_f32_e32 v9, v178, v76
	v_mul_f32_e32 v9, 0xbfb8aa3b, v9
	v_exp_f32_e32 v9, v9
	v_add_f32_e32 v8, 1.0, v8
	v_rcp_f32_e32 v8, v8
	v_add_f32_e32 v75, 1.0, v75
	v_add_f32_e32 v9, 1.0, v9
	v_rcp_f32_e32 v74, v9
	v_mul_f32_e32 v8, v180, v8
	v_exp_f32_e32 v9, v8
	v_add_f32_e32 v8, v176, v81
	v_mul_f32_e32 v8, 0xbfb8aa3b, v8
	v_exp_f32_e32 v8, v8
	v_rcp_f32_e32 v78, v75
	v_fma_f32 v75, v13, v14, v15
	v_mul_f32_e32 v13, v13, v11
	v_add_f32_e32 v8, 1.0, v8
	v_rcp_f32_e32 v8, v8
	v_mul_f32_e32 v15, v9, v13
	v_mul_f32_e32 v8, v180, v8
	v_exp_f32_e32 v81, v8
	v_fma_f32 v8, -v9, v9, 1.0
	v_max_f32_e32 v8, 0, v8
	v_sqrt_f32_e32 v8, v8
	s_nop 0
	v_pk_mul_f32 v[76:77], v[74:75], v[8:9]
	v_add_f32_e32 v9, v177, v70
	v_mul_f32_e32 v9, 0xbfb8aa3b, v9
	v_exp_f32_e32 v9, v9
	v_fmac_f32_e32 v77, v76, v140
	v_fma_f32 v8, -v81, v81, 1.0
	v_max_f32_e32 v8, 0, v8
	v_add_f32_e32 v9, 1.0, v9
	v_rcp_f32_e32 v9, v9
	v_sqrt_f32_e32 v80, v8
	v_mov_b32_e32 v79, v77
	v_mul_f32_e32 v74, v81, v15
	v_mul_f32_e32 v9, v181, v9
	v_exp_f32_e32 v76, v9
	v_pk_mul_f32 v[78:79], v[78:79], v[80:81]
	ds_bpermute_b32 v8, v0, v74
	v_fmac_f32_e32 v79, v78, v141
	v_fma_f32 v9, -v76, v76, 1.0
	v_max_f32_e32 v9, 0, v9
	v_sqrt_f32_e32 v70, v9
	v_add_f32_e32 v9, v177, v71
	v_mul_f32_e32 v9, 0xbfb8aa3b, v9
	v_exp_f32_e32 v9, v9
	ds_bpermute_b32 v80, v0, v79
	ds_bpermute_b32 v138, v0, v74 offset:64
	ds_bpermute_b32 v140, v0, v79 offset:64
	v_add_f32_e32 v9, 1.0, v9
	v_rcp_f32_e32 v9, v9
	ds_bpermute_b32 v188, v0, v74 offset:128
	ds_bpermute_b32 v190, v0, v79 offset:128
	ds_bpermute_b32 v192, v0, v74 offset:192
	v_mul_f32_e32 v9, v181, v9
	v_exp_f32_e32 v9, v9
	ds_bpermute_b32 v194, v0, v79 offset:192
	v_fma_f32 v71, -v9, v9, 1.0
	v_max_f32_e32 v71, 0, v71
	v_sqrt_f32_e32 v71, v71
	s_nop 0
	v_pk_mul_f32 v[66:67], v[66:67], v[70:71]
	s_nop 0
	v_pk_mul_f32 v[66:67], v[66:67], v[2:3]
	v_add_f32_e32 v2, v177, v72
	v_mul_f32_e32 v2, 0xbfb8aa3b, v2
	v_exp_f32_e32 v2, v2
	v_add_f32_e32 v3, v179, v68
	v_mul_f32_e32 v3, 0xbfb8aa3b, v3
	v_exp_f32_e32 v3, v3
	v_add_f32_e32 v2, 1.0, v2
	v_rcp_f32_e32 v2, v2
	v_rcp_f32_e32 v70, v69
	v_add_f32_e32 v3, 1.0, v3
	v_rcp_f32_e32 v68, v3
	v_mul_f32_e32 v2, v181, v2
	v_exp_f32_e32 v3, v2
	v_add_f32_e32 v2, v177, v73
	v_mul_f32_e32 v2, 0xbfb8aa3b, v2
	v_exp_f32_e32 v2, v2
	v_fma_f32 v69, v9, v66, v67
	v_mul_f32_e32 v67, v9, v76
	v_add_f32_e32 v2, 1.0, v2
	v_rcp_f32_e32 v2, v2
	s_nop 0
	v_mul_f32_e32 v2, v181, v2
	v_exp_f32_e32 v73, v2
	v_fma_f32 v2, -v3, v3, 1.0
	v_max_f32_e32 v2, 0, v2
	v_sqrt_f32_e32 v2, v2
	s_nop 0
	v_pk_mul_f32 v[196:197], v[68:69], v[2:3]
	v_fma_f32 v2, -v73, v73, 1.0
	v_max_f32_e32 v2, 0, v2
	v_sqrt_f32_e32 v72, v2
	v_fmac_f32_e32 v197, v196, v4
	v_mov_b32_e32 v71, v197
	v_mul_f32_e32 v68, v3, v67
	v_pk_mul_f32 v[70:71], v[70:71], v[72:73]
	v_pk_fma_f32 v[2:3], v[126:127], v[184:185], v[186:187]
	v_fmac_f32_e32 v71, v70, v5
	v_mul_f32_e32 v70, v73, v68
	ds_bpermute_b32 v9, v0, v70
	ds_bpermute_b32 v81, v0, v71
	ds_bpermute_b32 v139, v0, v70 offset:64
	ds_bpermute_b32 v141, v0, v71 offset:64
	ds_bpermute_b32 v189, v0, v70 offset:128
	ds_bpermute_b32 v191, v0, v71 offset:128
	s_waitcnt lgkmcnt(4)
	v_pk_fma_f32 v[72:73], v[16:17], v[8:9], v[80:81]
	ds_bpermute_b32 v193, v0, v70 offset:192
	s_waitcnt lgkmcnt(3)
	v_pk_fma_f32 v[80:81], v[72:73], v[138:139], v[140:141]
	ds_bpermute_b32 v195, v0, v71 offset:192
	s_waitcnt lgkmcnt(2)
; #define LAS __attribute__((address_space(3)))
; __device__ __forceinline__ unsigned cvt_pk_bf16(float lo, float hi) { unsigned r; asm volatile("v_cvt_pk_bf16_f32 %0, %1, %2" : "=v"(r) : "v"(lo), "v"(hi)); return r; }
; __device__ __forceinline__ float bflo(unsigned w) { return __uint_as_float(w << 16); }
; __device__ __forceinline__ float bfhi(unsigned w) { return __uint_as_float(w & 0xffff0000u); }
; __device__ __forceinline__ u32x4 pack8(const f32x4 a, const f32x4 b) { u32x4 w; w.x = cvt_pk_bf16(a[0], a[1]); w.y = cvt_pk_bf16(a[2], a[3]); w.z = cvt_pk_bf16(b[0], b[1]); w.w = cvt_pk_bf16(b[2], b[3]); return w; }
; template <int PASS> __device__ __forceinline__ void lru_wave_item(LAS unsigned char* lds, LAS unsigned char* vw, int b, int c, int h, const MixP& p, int lane, float (&Hrun)[8], bool cont) {
;     ...
;                 const float cin = fq == 0 ? c0 : (fq == 1 ? c1 : (fq == 2 ? c2 : c3));
;                 aR[n][0] = H0 + A0 * cin; aR[n][1] = H1 + A1 * cin; aR[n][2] = H2 + A2 * cin; aR[n][3] = H3 + A3 * cin;
;             }
;         }
;         if (PASS == 2) {
; #pragma unroll
;             for (int n = 0; n < 8; ++n)
; #pragma unroll
;                 for (int j = 0; j < 4; j += 2) { const unsigned w = cvt_pk_bf16(aR[n][j], aR[n][j + 1]);
;                     *(LAS unsigned short*)(vw + (4 * fq + j) * WROW + (16 * n + fr) * 2) = (unsigned short)(w & 0xffffu);
;                     *(LAS unsigned short*)(vw + (4 * fq + j + 1) * WROW + (16 * n + fr) * 2) = (unsigned short)(w >> 16); }
; #pragma unroll
;             for (int i = 0; i < 4; ++i) {
;                 const int t = fq + 4 * i; const size_t row = (size_t)(row0 + 16 * st + t);
;                 const u32x4 hh = *(const LAS u32x4*)(vw + t * WROW + cg * 16);
;                 const u32x4 g = *(const u32x4*)(p.P2 + row * P2W + h * 128 + cg * 8);
;                 const f32x4 o0 = (f32x4){bflo(hh.x) * bflo(g.x), bfhi(hh.x) * bfhi(g.x), bflo(hh.y) * bflo(g.y), bfhi(hh.y) * bfhi(g.y)};
;                 const f32x4 o1 = (f32x4){bflo(hh.z) * bflo(g.z), bfhi(hh.z) * bfhi(g.z), bflo(hh.w) * bflo(g.w), bfhi(hh.w) * bfhi(g.w)};
;                 *(u32x4*)(p.hl + row * LW + h * 128 + cg * 8) = pack8(o0, o1);
	v_pk_fma_f32 v[138:139], v[80:81], v[188:189], v[190:191]
	v_pk_fma_f32 v[4:5], v[106:107], v[116:117], v[128:129]
	v_cndmask_b32_e64 v0, v138, v80, s[8:9]
	v_cndmask_b32_e64 v0, v0, v72, s[6:7]
	v_cndmask_b32_e64 v0, v0, v16, s[4:5]
	v_fmac_f32_e32 v14, v11, v0
	v_fmac_f32_e32 v75, v13, v0
	v_fmac_f32_e32 v77, v15, v0
	v_fmac_f32_e32 v79, v74, v0
	v_cndmask_b32_e64 v0, v139, v81, s[8:9]
	v_cndmask_b32_e64 v0, v0, v73, s[6:7]
	v_cndmask_b32_e64 v0, v0, v17, s[4:5]
	v_fmac_f32_e32 v66, v76, v0
	v_fmac_f32_e32 v69, v67, v0
	v_fmac_f32_e32 v197, v68, v0
	v_fmac_f32_e32 v71, v70, v0
	v_cvt_pk_bf16_f32 v0, v130, v133
	ds_write_b16 v234, v0
	ds_write_b16_d16_hi v234, v0 offset:272
	v_cvt_pk_bf16_f32 v0, v135, v137
	ds_write_b16 v234, v0 offset:544
	ds_write_b16_d16_hi v234, v0 offset:816
	v_cvt_pk_bf16_f32 v0, v118, v121
	ds_write_b16 v234, v0 offset:32
	ds_write_b16_d16_hi v234, v0 offset:304
	v_cvt_pk_bf16_f32 v0, v123, v125
	ds_write_b16 v234, v0 offset:576
	ds_write_b16_d16_hi v234, v0 offset:848
	v_cvt_pk_bf16_f32 v0, v10, v111
	ds_write_b16 v234, v0 offset:64
	ds_write_b16_d16_hi v234, v0 offset:336
	v_cvt_pk_bf16_f32 v0, v113, v115
	ds_write_b16 v234, v0 offset:608
	ds_write_b16_d16_hi v234, v0 offset:880
	v_cvt_pk_bf16_f32 v0, v90, v93
	ds_write_b16 v234, v0 offset:96
	ds_write_b16_d16_hi v234, v0 offset:368
	v_cvt_pk_bf16_f32 v0, v103, v105
	ds_write_b16 v234, v0 offset:640
	ds_write_b16_d16_hi v234, v0 offset:912
	v_cvt_pk_bf16_f32 v0, v12, v95
	ds_write_b16 v234, v0 offset:128
	ds_write_b16_d16_hi v234, v0 offset:400
	v_cvt_pk_bf16_f32 v0, v97, v99
	ds_write_b16 v234, v0 offset:672
	ds_write_b16_d16_hi v234, v0 offset:944
	v_cvt_pk_bf16_f32 v0, v82, v85
	ds_write_b16 v234, v0 offset:160
	ds_write_b16_d16_hi v234, v0 offset:432
	v_cvt_pk_bf16_f32 v0, v87, v89
	ds_write_b16 v234, v0 offset:704
	ds_write_b16_d16_hi v234, v0 offset:976
	v_cvt_pk_bf16_f32 v0, v14, v75
	ds_write_b16 v234, v0 offset:192
	ds_write_b16_d16_hi v234, v0 offset:464
	v_cvt_pk_bf16_f32 v0, v77, v79
	ds_write_b16 v234, v0 offset:736
	ds_write_b16_d16_hi v234, v0 offset:1008
	v_cvt_pk_bf16_f32 v0, v66, v69
	ds_write_b16 v234, v0 offset:224
	ds_write_b16_d16_hi v234, v0 offset:496
	v_cvt_pk_bf16_f32 v0, v197, v71
	ds_write_b16 v234, v0 offset:768
	ds_write_b16_d16_hi v234, v0 offset:1040
	v_or_b32_e32 v0, s19, v203
	ds_read_b128 v[10:13], v235
	s_waitcnt lgkmcnt(14)
	v_pk_fma_f32 v[8:9], v[138:139], v[192:193], v[194:195]
	s_waitcnt lgkmcnt(0)
	v_lshlrev_b32_e32 v67, 16, v10
	v_and_b32_e32 v10, 0xffff0000, v10
	s_waitcnt vmcnt(11)
	v_lshlrev_b32_e32 v66, 16, v240
	v_and_b32_e32 v240, 0xffff0000, v240
	v_mul_f32_e32 v66, v66, v67
	v_mul_f32_e32 v10, v240, v10
	v_lshlrev_b32_e32 v240, 16, v241
	v_lshlrev_b32_e32 v67, 16, v11
	v_and_b32_e32 v241, 0xffff0000, v241
	v_and_b32_e32 v11, 0xffff0000, v11
	v_mul_f32_e32 v240, v240, v67
	v_mul_f32_e32 v11, v241, v11
	v_lshlrev_b32_e32 v241, 16, v242
	v_lshlrev_b32_e32 v67, 16, v12
	v_and_b32_e32 v242, 0xffff0000, v242
	v_and_b32_e32 v12, 0xffff0000, v12
	v_mul_f32_e32 v241, v241, v67
	v_mul_f32_e32 v12, v242, v12
	v_lshlrev_b32_e32 v242, 16, v243
	v_lshlrev_b32_e32 v67, 16, v13
	v_and_b32_e32 v243, 0xffff0000, v243
	v_and_b32_e32 v13, 0xffff0000, v13
	v_mul_f32_e32 v13, v243, v13
	v_cvt_pk_bf16_f32 v10, v66, v10
	v_cvt_pk_bf16_f32 v11, v240, v11
	v_cvt_pk_bf16_f32 v12, v241, v12
	v_mad_i64_i32 v[14:15], s[20:21], v0, s40, v[154:155]
	v_or_b32_e32 v0, s19, v225
	v_mul_f32_e32 v242, v242, v67
	v_cvt_pk_bf16_f32 v13, v242, v13
	global_store_dwordx4 v[14:15], v[10:13], off sc1
	ds_read_b128 v[10:13], v235 offset:1088
	s_waitcnt lgkmcnt(0)
; #define LAS __attribute__((address_space(3)))
; __device__ __forceinline__ float bflo(unsigned w) { return __uint_as_float(w << 16); }
; __device__ __forceinline__ float bfhi(unsigned w) { return __uint_as_float(w & 0xffff0000u); }
; __device__ __forceinline__ u32x4 pack8(const f32x4 a, const f32x4 b) { u32x4 w; w.x = cvt_pk_bf16(a[0], a[1]); w.y = cvt_pk_bf16(a[2], a[3]); w.z = cvt_pk_bf16(b[0], b[1]); w.w = cvt_pk_bf16(b[2], b[3]); return w; }
; template <int PASS> __device__ __forceinline__ void lru_wave_item(LAS unsigned char* lds, LAS unsigned char* vw, int b, int c, int h, const MixP& p, int lane, float (&Hrun)[8], bool cont) {
;     ...
;             for (int i = 0; i < 4; ++i) {
;                 const int t = fq + 4 * i; const size_t row = (size_t)(row0 + 16 * st + t);
;                 const u32x4 hh = *(const LAS u32x4*)(vw + t * WROW + cg * 16);
;                 const u32x4 g = *(const u32x4*)(p.P2 + row * P2W + h * 128 + cg * 8);
;                 const f32x4 o0 = (f32x4){bflo(hh.x) * bflo(g.x), bfhi(hh.x) * bfhi(g.x), bflo(hh.y) * bflo(g.y), bfhi(hh.y) * bfhi(g.y)};
;                 const f32x4 o1 = (f32x4){bflo(hh.z) * bflo(g.z), bfhi(hh.z) * bfhi(g.z), bflo(hh.w) * bflo(g.w), bfhi(hh.w) * bfhi(g.w)};
;                 *(u32x4*)(p.hl + row * LW + h * 128 + cg * 8) = pack8(o0, o1);
;             }
	v_lshlrev_b32_e32 v66, 16, v10
	v_and_b32_e32 v10, 0xffff0000, v10
	s_waitcnt vmcnt(11)
	v_lshlrev_b32_e32 v67, 16, v244
	v_and_b32_e32 v244, 0xffff0000, v244
	v_mul_f32_e32 v66, v67, v66
	v_mul_f32_e32 v10, v244, v10
	v_lshlrev_b32_e32 v244, 16, v11
	v_lshlrev_b32_e32 v67, 16, v245
	v_and_b32_e32 v245, 0xffff0000, v245
	v_and_b32_e32 v11, 0xffff0000, v11
	v_mul_f32_e32 v244, v67, v244
	v_mul_f32_e32 v11, v245, v11
	v_lshlrev_b32_e32 v245, 16, v12
	v_lshlrev_b32_e32 v67, 16, v246
	v_and_b32_e32 v246, 0xffff0000, v246
	v_and_b32_e32 v12, 0xffff0000, v12
	v_mul_f32_e32 v245, v67, v245
	v_mul_f32_e32 v12, v246, v12
	v_lshlrev_b32_e32 v246, 16, v13
	v_lshlrev_b32_e32 v67, 16, v247
	v_and_b32_e32 v247, 0xffff0000, v247
	v_and_b32_e32 v13, 0xffff0000, v13
	v_mul_f32_e32 v13, v247, v13
	v_cvt_pk_bf16_f32 v10, v66, v10
	v_cvt_pk_bf16_f32 v11, v244, v11
	v_cvt_pk_bf16_f32 v12, v245, v12
	v_mad_i64_i32 v[14:15], s[20:21], v0, s40, v[154:155]
	v_or_b32_e32 v0, s19, v226
	v_mul_f32_e32 v246, v67, v246
	v_cvt_pk_bf16_f32 v13, v246, v13
	global_store_dwordx4 v[14:15], v[10:13], off sc1
	ds_read_b128 v[10:13], v235 offset:2176
	s_waitcnt lgkmcnt(0)
	v_lshlrev_b32_e32 v66, 16, v10
	v_and_b32_e32 v10, 0xffff0000, v10
	s_waitcnt vmcnt(11)
	v_lshlrev_b32_e32 v67, 16, v248
	v_and_b32_e32 v248, 0xffff0000, v248
	v_mul_f32_e32 v66, v67, v66
	v_mul_f32_e32 v10, v248, v10
	v_lshlrev_b32_e32 v248, 16, v11
	v_lshlrev_b32_e32 v67, 16, v249
	v_and_b32_e32 v249, 0xffff0000, v249
	v_and_b32_e32 v11, 0xffff0000, v11
	v_mul_f32_e32 v248, v67, v248
	v_mul_f32_e32 v11, v249, v11
	v_lshlrev_b32_e32 v249, 16, v12
	v_lshlrev_b32_e32 v67, 16, v250
	v_and_b32_e32 v250, 0xffff0000, v250
	v_and_b32_e32 v12, 0xffff0000, v12
	v_mul_f32_e32 v249, v67, v249
	v_mul_f32_e32 v12, v250, v12
	v_lshlrev_b32_e32 v250, 16, v13
	v_lshlrev_b32_e32 v67, 16, v251
	v_and_b32_e32 v251, 0xffff0000, v251
	v_and_b32_e32 v13, 0xffff0000, v13
	v_mul_f32_e32 v13, v251, v13
	v_cvt_pk_bf16_f32 v10, v66, v10
	v_cvt_pk_bf16_f32 v11, v248, v11
	v_cvt_pk_bf16_f32 v12, v249, v12
	v_mad_i64_i32 v[14:15], s[20:21], v0, s40, v[154:155]
	v_or_b32_e32 v0, s19, v227
	v_mul_f32_e32 v250, v67, v250
	v_cvt_pk_bf16_f32 v13, v250, v13
	global_store_dwordx4 v[14:15], v[10:13], off sc1
	ds_read_b128 v[10:13], v235 offset:3264
	s_mov_b32 s19, 16
	s_waitcnt lgkmcnt(0)
	v_lshlrev_b32_e32 v66, 16, v10
	v_and_b32_e32 v10, 0xffff0000, v10
	s_waitcnt vmcnt(10)
	v_lshlrev_b32_e32 v67, 16, v206
	v_and_b32_e32 v206, 0xffff0000, v206
	v_mul_f32_e32 v66, v67, v66
	v_mul_f32_e32 v10, v206, v10
	v_lshlrev_b32_e32 v206, 16, v11
	v_lshlrev_b32_e32 v67, 16, v207
	v_and_b32_e32 v207, 0xffff0000, v207
	v_and_b32_e32 v11, 0xffff0000, v11
	v_mul_f32_e32 v206, v67, v206
	v_mul_f32_e32 v11, v207, v11
	v_lshlrev_b32_e32 v207, 16, v12
	v_lshlrev_b32_e32 v67, 16, v210
	v_and_b32_e32 v210, 0xffff0000, v210
	v_and_b32_e32 v12, 0xffff0000, v12
	v_mul_f32_e32 v207, v67, v207
	v_mul_f32_e32 v12, v210, v12
	v_lshlrev_b32_e32 v210, 16, v13
	v_lshlrev_b32_e32 v67, 16, v211
	v_and_b32_e32 v211, 0xffff0000, v211
	v_and_b32_e32 v13, 0xffff0000, v13
	v_mul_f32_e32 v13, v211, v13
	v_mul_f32_e32 v210, v67, v210
	v_cvt_pk_bf16_f32 v10, v66, v10
	v_cvt_pk_bf16_f32 v11, v206, v11
	v_cvt_pk_bf16_f32 v12, v207, v12
	v_cvt_pk_bf16_f32 v13, v210, v13
	v_mad_i64_i32 v[14:15], s[20:21], v0, s40, v[154:155]
	global_store_dwordx4 v[14:15], v[10:13], off sc1
	v_mov_b64_e32 v[16:17], v[8:9]
	v_mov_b64_e32 v[14:15], v[6:7]
	v_mov_b64_e32 v[12:13], v[4:5]
	v_mov_b64_e32 v[10:11], v[2:3]
	s_cbranch_vccnz .LBB0_818
	s_add_i32 s1, s1, 1
	s_cmp_ge_i32 s1, s10
	s_cbranch_scc0 .LBB0_811
	s_branch .LBB0_797

;     __host__ __device__ bool next(int i, Unit& u) const {
;         const long L = (long)i * G + c; if (L >= nwg) return false;
;         int wgid = (int)L; { const int q = nwg / NXCD, r = nwg % NXCD, xcd = wgid % NXCD, off = wgid / NXCD; wgid = (xcd < r ? xcd * (q + 1) : r * (q + 1) + (xcd - r) * q) + off; }
.LBB0_884:
	s_add_i32 s39, s39, 1
	v_readlane_b32 s2, v253, 52
	s_mul_i32 s2, s39, s2
	s_mul_hi_u32 s3, s39, s66
	s_add_i32 s3, s3, s2
	s_mul_i32 s2, s39, s66
	s_add_u32 s10, s2, s22
	s_addc_u32 s11, s3, s23
	v_mov_b64_e32 v[206:207], 0xff
	v_mov_b64_e32 v[210:211], 0x100
	v_cmp_gt_i64_e32 vcc, s[10:11], v[206:207]
	v_cmp_lt_i64_e64 s[2:3], s[10:11], v[210:211]
	s_cbranch_vccnz .LBB0_890
	s_ashr_i32 s6, s10, 31
	s_lshr_b32 s6, s6, 29
	s_add_i32 s8, s10, s6
	s_and_b32 s6, s8, -8
	s_sub_i32 s9, s10, s6
	s_cmp_gt_i32 s9, -1
	s_mov_b64 s[6:7], -1
	s_cbranch_scc0 .LBB0_887
	s_lshl_b32 s10, s9, 5
	s_mov_b64 s[6:7], 0

;     __host__ __device__ bool next(int i, Unit& u) const {
;         const long L = (long)i * G + c; if (L >= nwg) return false;
;         int wgid = (int)L; { const int q = nwg / NXCD, r = nwg % NXCD, xcd = wgid % NXCD, off = wgid / NXCD; wgid = (xcd < r ? xcd * (q + 1) : r * (q + 1) + (xcd - r) * q) + off; }
.LBB0_908:
	s_add_i32 s29, s29, 1
	v_readlane_b32 s2, v253, 52
	s_mul_i32 s2, s29, s2
	s_mul_hi_u32 s3, s29, s66
	s_add_i32 s3, s3, s2
	s_mul_i32 s2, s29, s66
	s_add_u32 s2, s2, s18
	s_addc_u32 s3, s3, s19
	v_mov_b64_e32 v[206:207], 0xff
	v_mov_b64_e32 v[210:211], 0x100
	v_cmp_gt_i64_e32 vcc, s[2:3], v[206:207]
	v_cmp_lt_i64_e64 s[4:5], s[2:3], v[210:211]
	s_cbranch_vccnz .LBB0_914
	s_ashr_i32 s3, s2, 31
	s_lshr_b32 s3, s3, 29
	s_add_i32 s8, s2, s3
	s_and_b32 s3, s8, -8
	s_sub_i32 s9, s2, s3
	s_cmp_gt_i32 s9, -1
	s_mov_b64 s[2:3], -1
	s_cbranch_scc0 .LBB0_911
	s_lshl_b32 s14, s9, 5
	s_mov_b64 s[2:3], 0

;     __host__ __device__ bool next(int i, Unit& u) const {
;         const long L = (long)i * G + c; if (L >= nwg) return false;
;         int wgid = (int)L; { const int q = nwg / NXCD, r = nwg % NXCD, xcd = wgid % NXCD, off = wgid / NXCD; wgid = (xcd < r ? xcd * (q + 1) : r * (q + 1) + (xcd - r) * q) + off; }
.LBB0_1043:
	s_add_i32 s46, s46, 1
	v_readlane_b32 s4, v253, 52
	s_mul_i32 s4, s46, s4
	s_mul_hi_u32 s5, s46, s66
	s_add_i32 s5, s5, s4
	s_mul_i32 s4, s46, s66
	s_add_u32 s14, s4, s28
	s_addc_u32 s15, s5, s47
	v_mov_b64_e32 v[206:207], 0xff
	v_mov_b64_e32 v[210:211], 0x100
	v_cmp_gt_i64_e32 vcc, s[14:15], v[206:207]
	v_cmp_lt_i64_e64 s[4:5], s[14:15], v[210:211]
	s_cbranch_vccnz .LBB0_1049
	s_ashr_i32 s10, s14, 31
	s_lshr_b32 s10, s10, 29
	s_add_i32 s12, s14, s10
	s_and_b32 s10, s12, -8
	s_sub_i32 s13, s14, s10
	s_cmp_gt_i32 s13, -1
	s_mov_b64 s[10:11], -1
	s_cbranch_scc0 .LBB0_1046
	s_lshl_b32 s14, s13, 5
	s_mov_b64 s[10:11], 0

; __global__ void __launch_bounds__(512, 2) fwd_mega(Args a) {
	.amdhsa_kernel _Z8fwd_mega4Args
		.amdhsa_group_segment_fixed_size 0
		.amdhsa_private_segment_fixed_size 0
		.amdhsa_kernarg_size 456
		.amdhsa_user_sgpr_count 2
		.amdhsa_user_sgpr_dispatch_ptr 0
		.amdhsa_user_sgpr_queue_ptr 0
		.amdhsa_user_sgpr_kernarg_segment_ptr 1
		.amdhsa_user_sgpr_dispatch_id 0
		.amdhsa_user_sgpr_kernarg_preload_length 0
		.amdhsa_user_sgpr_kernarg_preload_offset 0
		.amdhsa_user_sgpr_private_segment_size 0
		.amdhsa_uses_dynamic_stack 0
		.amdhsa_enable_private_segment 0
		.amdhsa_system_sgpr_workgroup_id_x 1
		.amdhsa_system_sgpr_workgroup_id_y 0
		.amdhsa_system_sgpr_workgroup_id_z 0
		.amdhsa_system_sgpr_workgroup_info 0
		.amdhsa_system_vgpr_workitem_id 2
		.amdhsa_next_free_vgpr 256
		.amdhsa_next_free_sgpr 102
		.amdhsa_accum_offset 256
		.amdhsa_reserve_vcc 1
		.amdhsa_float_round_mode_32 0
		.amdhsa_float_round_mode_16_64 0
		.amdhsa_float_denorm_mode_32 3
		.amdhsa_float_denorm_mode_16_64 3
		.amdhsa_dx10_clamp 1
		.amdhsa_ieee_mode 1
		.amdhsa_fp16_overflow 0
		.amdhsa_tg_split 0
		.amdhsa_exception_fp_ieee_invalid_op 0
		.amdhsa_exception_fp_denorm_src 0
		.amdhsa_exception_fp_ieee_div_zero 0
		.amdhsa_exception_fp_ieee_overflow 0
		.amdhsa_exception_fp_ieee_underflow 0
		.amdhsa_exception_fp_ieee_inexact 0
		.amdhsa_exception_int_div_zero 0
	.end_amdhsa_kernel

; __global__ void __launch_bounds__(512, 2) fwd_mega(Args a) {
amdhsa.kernels:
  - .agpr_count:     0
    .args:
      - .offset:         0
        .size:           200
        .value_kind:     by_value
      - .offset:         200
        .size:           4
        .value_kind:     hidden_block_count_x
      - .offset:         204
        .size:           4
        .value_kind:     hidden_block_count_y
      - .offset:         208
        .size:           4
        .value_kind:     hidden_block_count_z
      - .offset:         212
        .size:           2
        .value_kind:     hidden_group_size_x
      - .offset:         214
        .size:           2
        .value_kind:     hidden_group_size_y
      - .offset:         216
        .size:           2
        .value_kind:     hidden_group_size_z
      - .offset:         218
        .size:           2
        .value_kind:     hidden_remainder_x
      - .offset:         220
        .size:           2
        .value_kind:     hidden_remainder_y
      - .offset:         222
        .size:           2
        .value_kind:     hidden_remainder_z
      - .offset:         240
        .size:           8
        .value_kind:     hidden_global_offset_x
      - .offset:         248
        .size:           8
        .value_kind:     hidden_global_offset_y
      - .offset:         256
        .size:           8
        .value_kind:     hidden_global_offset_z
      - .offset:         264
        .size:           2
        .value_kind:     hidden_grid_dims
      - .offset:         288
        .size:           8
        .value_kind:     hidden_multigrid_sync_arg
      - .offset:         320
        .size:           4
        .value_kind:     hidden_dynamic_lds_size
    .group_segment_fixed_size: 0
    .kernarg_segment_align: 8
    .kernarg_segment_size: 456
    .language:       OpenCL C
    .language_version:
      - 2
      - 0
    .max_flat_workgroup_size: 512
    .name:           _Z8fwd_mega4Args
    .private_segment_fixed_size: 0
    .sgpr_count:     108
    .sgpr_spill_count: 140
    .symbol:         _Z8fwd_mega4Args.kd
    .uniform_work_group_size: 1
    .uses_dynamic_stack: false
    .vgpr_count:     256
    .vgpr_spill_count: 0
    .wavefront_size: 64
